# SEAM 2 as a split barrier: in-proj tiles reordered (gate tiles last), write-through stores for the tiles P3/P5 read, count-in one tile before the end, check after it
# speedup vs baseline: 1.0083x; 1.0083x over previous
.LBB0_134:
	s_add_i32 s79, s79, 1
	s_cmp_lg_u32 s79, 6
	s_cbranch_scc1 .Lp2_noarr
	s_mov_b64 s[100:101], exec
	v_readlane_b32 s4, v246, 2
	v_readlane_b32 s5, v246, 3
	s_and_b64 s[4:5], s[100:101], s[4:5]
	s_mov_b64 exec, s[4:5]
	s_cbranch_execz .Lp2_arr_done
	v_mov_b32_e32 v250, 0
	v_mov_b32_e32 v251, 1
	s_add_u32 s4, s92, 0x55000
	s_addc_u32 s5, s93, 0
	global_atomic_add v250, v251, s[4:5]
.Lp2_arr_done:
	s_mov_b64 exec, s[100:101]
.Lp2_noarr:
	s_lshl_b32 s99, s79, 2
	s_lshr_b32 s99, 0x76524310, s99
	s_and_b32 s99, s99, 15
	s_mul_i32 s4, s99, s82
	s_mul_hi_u32 s5, s99, s3
	s_add_i32 s5, s5, s4
	s_mul_i32 s4, s99, s3
	s_add_u32 s34, s4, s2
	s_addc_u32 s35, s5, s83
	v_cmp_gt_i64_e32 vcc, s[34:35], v[146:147]
	v_cmp_lt_i64_e64 s[4:5], s[34:35], v[144:145]
	s_cbranch_vccnz .LBB0_136
	s_ashr_i32 s28, s34, 31
	s_lshr_b32 s28, s28, 29
	s_add_i32 s28, s34, s28
	s_ashr_i32 s29, s28, 3
	s_and_b32 s28, s28, -8
	s_sub_i32 s28, s34, s28
	s_cmp_lt_i32 s28, 0
	s_movk_i32 s30, 0xc1
	s_cselect_b32 s30, s30, 0xc0
	s_mul_i32 s28, s28, s30
	s_add_i32 s28, s28, s29
	s_mul_hi_i32 s29, s28, 0x2aaaaaab
	s_lshr_b32 s30, s29, 31
	s_ashr_i32 s29, s29, 4
	s_add_i32 s29, s29, s30
	s_lshl_b32 s30, s29, 2
	s_sub_i32 s31, 64, s30
	s_min_i32 s31, s31, 4
	s_abs_i32 s34, s31
	v_cvt_f32_u32_e32 v2, s34
	s_sub_i32 s36, 0, s34
	s_mulk_i32 s29, 0x60
	s_sub_i32 s29, s28, s29
	v_rcp_iflag_f32_e32 v2, v2
	s_abs_i32 s28, s29
	s_xor_b32 s35, s29, s31
	s_ashr_i32 s35, s35, 31
	v_mul_f32_e32 v2, 0x4f7ffffe, v2
	v_cvt_u32_f32_e32 v2, v2
	s_nop 0
	v_readfirstlane_b32 s37, v2
	s_mul_i32 s36, s36, s37
	s_mul_hi_u32 s36, s37, s36
	s_add_i32 s37, s37, s36
	s_mul_hi_u32 s36, s28, s37
	s_mul_i32 s37, s36, s34
	s_sub_i32 s28, s28, s37
	s_add_i32 s39, s36, 1
	s_sub_i32 s37, s28, s34
	s_cmp_ge_u32 s28, s34
	s_cselect_b32 s36, s39, s36
	s_cselect_b32 s28, s37, s28
	s_add_i32 s37, s36, 1
	s_cmp_ge_u32 s28, s34
	s_cselect_b32 s28, s37, s36
	s_xor_b32 s28, s28, s35
	s_sub_i32 s28, s28, s35
	s_mul_i32 s31, s28, s31
	s_sub_i32 s29, s29, s31
	s_add_i32 s30, s30, s29

.LBB0_156:
	s_lshl_b32 s31, s38, 8
	s_and_b32 s31, s31, 0x300
	v_or_b32_e32 v138, s31, v158
	v_lshlrev_b32_e32 v138, 1, v138
	v_lshl_add_u32 v150, s40, 8, v156
	s_cmp_lt_i32 s29, 4
	v_lshl_add_u64 v[148:149], s[46:47], 0, v[138:139]
	s_mov_b64 s[38:39], -1
	s_cbranch_scc0 .LBB0_185
	s_cmp_eq_u32 s29, 3
	s_cselect_b64 s[38:39], -1, 0
	s_or_b64 s[38:39], s[42:43], s[38:39]
	s_mov_b64 s[44:45], -1
	s_mov_b64 s[40:41], 0
	s_cmp_lt_i32 s29, 2
	s_mov_b64 s[42:43], 0
	s_cbranch_scc1 .LBB0_161
	s_cmp_eq_u32 s29, 2
	s_mov_b64 s[42:43], -1
	s_cbranch_scc0 .LBB0_160
	s_and_b64 s[42:43], s[38:39], exec
	v_ashrrev_i32_e32 v151, 31, v150
	s_cselect_b32 s31, 11, 10
	v_lshlrev_b64 v[152:153], s31, v[150:151]
	v_lshl_add_u64 v[164:165], v[152:153], 1, v[148:149]
	v_cvt_pk_bf16_f32 v152, v126, v127
	v_cvt_pk_bf16_f32 v153, v128, v129
	v_cvt_pk_bf16_f32 v154, v122, v123
	v_cvt_pk_bf16_f32 v155, v124, v125
	global_store_dwordx4 v[164:165], v[152:155], off sc1
	s_mov_b64 s[42:43], 0
	s_nop 0
	v_cvt_pk_bf16_f32 v152, v118, v119
	v_cvt_pk_bf16_f32 v153, v120, v121
	v_cvt_pk_bf16_f32 v154, v114, v115
	v_cvt_pk_bf16_f32 v155, v116, v117
	global_store_dwordx4 v[164:165], v[152:155], off offset:256 sc1
	s_nop 1
	v_or_b32_e32 v152, 16, v150
	v_ashrrev_i32_e32 v153, 31, v152
	v_lshlrev_b64 v[152:153], s31, v[152:153]
	v_lshl_add_u64 v[164:165], v[152:153], 1, v[148:149]
	v_cvt_pk_bf16_f32 v152, v110, v111
	v_cvt_pk_bf16_f32 v153, v112, v113
	v_cvt_pk_bf16_f32 v154, v106, v107
	v_cvt_pk_bf16_f32 v155, v108, v109
	global_store_dwordx4 v[164:165], v[152:155], off sc1
	s_nop 1
	v_cvt_pk_bf16_f32 v152, v102, v103
	v_cvt_pk_bf16_f32 v153, v104, v105
	v_cvt_pk_bf16_f32 v154, v98, v99
	v_cvt_pk_bf16_f32 v155, v100, v101
	global_store_dwordx4 v[164:165], v[152:155], off offset:256 sc1
	s_nop 1
	v_or_b32_e32 v152, 32, v150
	v_ashrrev_i32_e32 v153, 31, v152
	v_lshlrev_b64 v[152:153], s31, v[152:153]
	v_lshl_add_u64 v[164:165], v[152:153], 1, v[148:149]
	v_cvt_pk_bf16_f32 v152, v94, v95
	v_cvt_pk_bf16_f32 v153, v96, v97
	v_cvt_pk_bf16_f32 v154, v90, v91
	v_cvt_pk_bf16_f32 v155, v92, v93
	global_store_dwordx4 v[164:165], v[152:155], off sc1
	s_nop 1
	v_cvt_pk_bf16_f32 v152, v86, v87
	v_cvt_pk_bf16_f32 v153, v88, v89
	v_cvt_pk_bf16_f32 v154, v82, v83
	v_cvt_pk_bf16_f32 v155, v84, v85
	global_store_dwordx4 v[164:165], v[152:155], off offset:256 sc1
	s_nop 1
	v_or_b32_e32 v152, 48, v150
	v_ashrrev_i32_e32 v153, 31, v152
	v_lshlrev_b64 v[152:153], s31, v[152:153]
	v_lshl_add_u64 v[164:165], v[152:153], 1, v[148:149]
	v_cvt_pk_bf16_f32 v152, v78, v79
	v_cvt_pk_bf16_f32 v153, v80, v81
	v_cvt_pk_bf16_f32 v154, v74, v75
	v_cvt_pk_bf16_f32 v155, v76, v77
	global_store_dwordx4 v[164:165], v[152:155], off sc1
	s_nop 1
	v_cvt_pk_bf16_f32 v152, v70, v71
	v_cvt_pk_bf16_f32 v153, v72, v73
	v_cvt_pk_bf16_f32 v154, v66, v67
	v_cvt_pk_bf16_f32 v155, v68, v69
	global_store_dwordx4 v[164:165], v[152:155], off offset:256 sc1
	s_nop 1
	v_add_u32_e32 v152, 0x80, v150
	v_ashrrev_i32_e32 v153, 31, v152
	v_lshlrev_b64 v[152:153], s31, v[152:153]
	v_lshl_add_u64 v[164:165], v[152:153], 1, v[148:149]
	v_cvt_pk_bf16_f32 v152, v62, v63
	v_cvt_pk_bf16_f32 v153, v64, v65
	v_cvt_pk_bf16_f32 v154, v58, v59
	v_cvt_pk_bf16_f32 v155, v60, v61
	global_store_dwordx4 v[164:165], v[152:155], off sc1
	s_nop 1
	v_cvt_pk_bf16_f32 v152, v54, v55
	v_cvt_pk_bf16_f32 v153, v56, v57
	v_cvt_pk_bf16_f32 v154, v50, v51
	v_cvt_pk_bf16_f32 v155, v52, v53
	global_store_dwordx4 v[164:165], v[152:155], off offset:256 sc1
	s_nop 1
	v_add_u32_e32 v152, 0x90, v150
	v_ashrrev_i32_e32 v153, 31, v152
	v_lshlrev_b64 v[152:153], s31, v[152:153]
	v_lshl_add_u64 v[164:165], v[152:153], 1, v[148:149]
	v_cvt_pk_bf16_f32 v152, v46, v47
	v_cvt_pk_bf16_f32 v153, v48, v49
	v_cvt_pk_bf16_f32 v154, v42, v43
	v_cvt_pk_bf16_f32 v155, v44, v45
	global_store_dwordx4 v[164:165], v[152:155], off sc1
	s_nop 1
	v_cvt_pk_bf16_f32 v152, v38, v39
	v_cvt_pk_bf16_f32 v153, v40, v41
	v_cvt_pk_bf16_f32 v154, v34, v35
	v_cvt_pk_bf16_f32 v155, v36, v37
	global_store_dwordx4 v[164:165], v[152:155], off offset:256 sc1
	s_nop 1
	v_add_u32_e32 v152, 0xa0, v150
	v_ashrrev_i32_e32 v153, 31, v152
	v_lshlrev_b64 v[152:153], s31, v[152:153]
	v_lshl_add_u64 v[164:165], v[152:153], 1, v[148:149]
	v_cvt_pk_bf16_f32 v152, v30, v31
	v_cvt_pk_bf16_f32 v153, v32, v33
	v_cvt_pk_bf16_f32 v154, v26, v27
	v_cvt_pk_bf16_f32 v155, v28, v29
	global_store_dwordx4 v[164:165], v[152:155], off sc1
	s_nop 1
	v_cvt_pk_bf16_f32 v152, v22, v23
	v_cvt_pk_bf16_f32 v153, v24, v25
	v_cvt_pk_bf16_f32 v154, v18, v19
	v_cvt_pk_bf16_f32 v155, v20, v21
	global_store_dwordx4 v[164:165], v[152:155], off offset:256 sc1
	s_nop 1
	v_add_u32_e32 v152, 0xb0, v150
	v_ashrrev_i32_e32 v153, 31, v152
	v_lshlrev_b64 v[152:153], s31, v[152:153]
	v_lshl_add_u64 v[164:165], v[152:153], 1, v[148:149]
	v_cvt_pk_bf16_f32 v152, v14, v15
	v_cvt_pk_bf16_f32 v153, v16, v17
	v_cvt_pk_bf16_f32 v154, v10, v11
	v_cvt_pk_bf16_f32 v155, v12, v13
	global_store_dwordx4 v[164:165], v[152:155], off sc1
	s_nop 1
	v_cvt_pk_bf16_f32 v152, v6, v7
	v_cvt_pk_bf16_f32 v153, v8, v9
	v_cvt_pk_bf16_f32 v154, v2, v3
	v_cvt_pk_bf16_f32 v155, v4, v5
	global_store_dwordx4 v[164:165], v[152:155], off offset:256 sc1

.LBB0_163:
	v_mul_f32_e32 v138, v126, v126
	v_mul_f32_e32 v151, v122, v122
	v_mul_f32_e32 v152, v127, v127
	v_mul_f32_e32 v153, v123, v123
	v_mul_f32_e32 v154, v128, v128
	v_mul_f32_e32 v155, v124, v124
	v_mul_f32_e32 v164, v129, v129
	v_mul_f32_e32 v165, v125, v125
	v_mul_f32_e32 v166, v118, v118
	v_mul_f32_e32 v167, v114, v114
	v_mul_f32_e32 v168, v119, v119
	v_mul_f32_e32 v169, v115, v115
	v_mul_f32_e32 v170, v120, v120
	v_mul_f32_e32 v171, v116, v116
	v_mul_f32_e32 v172, v121, v121
	v_mul_f32_e32 v173, v117, v117
	v_mul_f32_e32 v174, v110, v110
	v_mul_f32_e32 v175, v106, v106
	v_mul_f32_e32 v176, v111, v111
	v_mul_f32_e32 v177, v107, v107
	v_mul_f32_e32 v178, v112, v112
	v_mul_f32_e32 v179, v108, v108
	v_mul_f32_e32 v180, v113, v113
	v_mul_f32_e32 v181, v109, v109
	v_mul_f32_e32 v182, v102, v102
	v_mul_f32_e32 v183, v98, v98
	v_mul_f32_e32 v184, v103, v103
	v_mul_f32_e32 v185, v99, v99
	v_mul_f32_e32 v186, v104, v104
	v_mul_f32_e32 v187, v100, v100
	v_mul_f32_e32 v188, v105, v105
	v_mul_f32_e32 v189, v101, v101
	v_mul_f32_e32 v190, v94, v94
	v_mul_f32_e32 v191, v90, v90
	v_mul_f32_e32 v192, v95, v95
	v_mul_f32_e32 v193, v91, v91
	v_mul_f32_e32 v210, v96, v96
	v_mul_f32_e32 v211, v92, v92
	v_mul_f32_e32 v229, v97, v97
	v_mul_f32_e32 v230, v93, v93
	v_mul_f32_e32 v231, v86, v86
	v_mul_f32_e32 v232, v82, v82
	v_mul_f32_e32 v233, v87, v87
	v_mul_f32_e32 v234, v83, v83
	v_mul_f32_e32 v235, v88, v88
	v_mul_f32_e32 v236, v84, v84
	v_mul_f32_e32 v237, v89, v89
	v_mul_f32_e32 v238, v85, v85
	s_andn2_b64 vcc, exec, s[42:43]
	v_fmamk_f32 v228, v138, 0xbdd2d3e8, v162
	v_fmamk_f32 v227, v151, 0xbdd2d3e8, v162
	v_fmamk_f32 v226, v152, 0xbdd2d3e8, v162
	v_fmamk_f32 v225, v153, 0xbdd2d3e8, v162
	v_fmamk_f32 v224, v154, 0xbdd2d3e8, v162
	v_fmamk_f32 v223, v155, 0xbdd2d3e8, v162
	v_fmamk_f32 v222, v164, 0xbdd2d3e8, v162
	v_fmamk_f32 v221, v165, 0xbdd2d3e8, v162
	v_fmamk_f32 v220, v166, 0xbdd2d3e8, v162
	v_fmamk_f32 v219, v167, 0xbdd2d3e8, v162
	v_fmamk_f32 v218, v168, 0xbdd2d3e8, v162
	v_fmamk_f32 v217, v169, 0xbdd2d3e8, v162
	v_fmamk_f32 v216, v170, 0xbdd2d3e8, v162
	v_fmamk_f32 v215, v171, 0xbdd2d3e8, v162
	v_fmamk_f32 v155, v172, 0xbdd2d3e8, v162
	v_fmamk_f32 v154, v173, 0xbdd2d3e8, v162
	v_fmamk_f32 v214, v174, 0xbdd2d3e8, v162
	v_fmamk_f32 v213, v175, 0xbdd2d3e8, v162
	v_fmamk_f32 v212, v176, 0xbdd2d3e8, v162
	v_fmamk_f32 v209, v177, 0xbdd2d3e8, v162
	v_fmamk_f32 v208, v178, 0xbdd2d3e8, v162
	v_fmamk_f32 v207, v179, 0xbdd2d3e8, v162
	v_fmamk_f32 v206, v180, 0xbdd2d3e8, v162
	v_fmamk_f32 v205, v181, 0xbdd2d3e8, v162
	v_fmamk_f32 v204, v182, 0xbdd2d3e8, v162
	v_fmamk_f32 v203, v183, 0xbdd2d3e8, v162
	v_fmamk_f32 v202, v184, 0xbdd2d3e8, v162
	v_fmamk_f32 v201, v185, 0xbdd2d3e8, v162
	v_fmamk_f32 v200, v186, 0xbdd2d3e8, v162
	v_fmamk_f32 v199, v187, 0xbdd2d3e8, v162
	v_fmamk_f32 v198, v188, 0xbdd2d3e8, v162
	v_fmamk_f32 v197, v189, 0xbdd2d3e8, v162
	v_fmamk_f32 v196, v190, 0xbdd2d3e8, v162
	v_fmamk_f32 v195, v191, 0xbdd2d3e8, v162
	v_fmamk_f32 v194, v192, 0xbdd2d3e8, v162
	v_fmamk_f32 v193, v193, 0xbdd2d3e8, v162
	v_fmamk_f32 v192, v210, 0xbdd2d3e8, v162
	v_fmamk_f32 v191, v211, 0xbdd2d3e8, v162
	v_fmamk_f32 v190, v229, 0xbdd2d3e8, v162
	v_fmamk_f32 v189, v230, 0xbdd2d3e8, v162
	v_fmamk_f32 v188, v231, 0xbdd2d3e8, v162
	v_fmamk_f32 v187, v232, 0xbdd2d3e8, v162
	v_fmamk_f32 v186, v233, 0xbdd2d3e8, v162
	v_fmamk_f32 v185, v234, 0xbdd2d3e8, v162
	v_fmamk_f32 v184, v235, 0xbdd2d3e8, v162
	v_fmamk_f32 v183, v236, 0xbdd2d3e8, v162
	v_fmamk_f32 v182, v237, 0xbdd2d3e8, v162
	v_fmamk_f32 v181, v238, 0xbdd2d3e8, v162
	v_mul_f32_e32 v180, v78, v78
	v_mul_f32_e32 v179, v74, v74
	v_mul_f32_e32 v178, v79, v79
	v_mul_f32_e32 v177, v75, v75
	v_mul_f32_e32 v176, v80, v80
	v_mul_f32_e32 v175, v76, v76
	v_mul_f32_e32 v174, v81, v81
	v_mul_f32_e32 v173, v77, v77
	v_mul_f32_e32 v172, v70, v70
	v_mul_f32_e32 v171, v66, v66
	v_mul_f32_e32 v170, v71, v71
	v_mul_f32_e32 v169, v67, v67
	v_mul_f32_e32 v168, v72, v72
	v_mul_f32_e32 v167, v68, v68
	v_mul_f32_e32 v166, v73, v73
	v_mul_f32_e32 v165, v69, v69
	v_add_u32_e32 v152, 0x80, v150
	v_mul_f32_e32 v164, v62, v62
	v_mul_f32_e32 v138, v58, v58
	s_cbranch_vccnz .LBB0_165
	s_and_b64 s[40:41], s[38:39], exec
	v_ashrrev_i32_e32 v151, 31, v150
	s_cselect_b32 s29, 11, 10
	v_lshlrev_b64 v[210:211], s29, v[150:151]
	v_mul_f32_e32 v151, v126, v228
	v_exp_f32_e32 v151, v151
	v_mul_f32_e32 v153, v122, v227
	v_exp_f32_e32 v153, v153
	v_mul_f32_e32 v229, v123, v225
	v_add_f32_e32 v151, 1.0, v151
	v_rcp_f32_e32 v230, v151
	v_add_f32_e32 v151, 1.0, v153
	v_mul_f32_e32 v153, v127, v226
	v_exp_f32_e32 v153, v153
	v_exp_f32_e32 v229, v229
	v_rcp_f32_e32 v232, v151
	v_lshl_add_u64 v[210:211], v[210:211], 1, v[148:149]
	v_add_f32_e32 v151, 1.0, v153
	v_mul_f32_e32 v153, v128, v224
	v_rcp_f32_e32 v231, v151
	v_add_f32_e32 v151, 1.0, v229
	v_exp_f32_e32 v153, v153
	v_mul_f32_e32 v229, v124, v223
	v_exp_f32_e32 v229, v229
	v_rcp_f32_e32 v233, v151
	v_add_f32_e32 v151, 1.0, v153
	v_mul_f32_e32 v153, v129, v222
	v_rcp_f32_e32 v234, v151
	v_add_f32_e32 v151, 1.0, v229
	v_exp_f32_e32 v153, v153
	v_mul_f32_e32 v229, v125, v221
	v_exp_f32_e32 v229, v229
	v_rcp_f32_e32 v236, v151
	v_add_f32_e32 v151, 1.0, v153
	v_rcp_f32_e32 v235, v151
	v_add_f32_e32 v151, 1.0, v229
	v_rcp_f32_e32 v237, v151
	v_mul_f32_e32 v151, v118, v220
	v_exp_f32_e32 v151, v151
	v_mul_f32_e32 v153, v114, v219
	v_exp_f32_e32 v153, v153
	v_pk_mul_f32 v[230:231], v[126:127], v[230:231]
	v_pk_mul_f32 v[232:233], v[122:123], v[232:233]
	v_pk_mul_f32 v[234:235], v[128:129], v[234:235]
	v_pk_mul_f32 v[236:237], v[124:125], v[236:237]
	v_cvt_pk_bf16_f32 v230, v230, v231
	v_cvt_pk_bf16_f32 v231, v234, v235
	v_cvt_pk_bf16_f32 v232, v232, v233
	v_cvt_pk_bf16_f32 v233, v236, v237
	v_add_f32_e32 v151, 1.0, v151
	global_store_dwordx4 v[210:211], v[230:233], off sc1
	v_mul_f32_e32 v229, v115, v217
	v_exp_f32_e32 v229, v229
	v_rcp_f32_e32 v230, v151
	v_add_f32_e32 v151, 1.0, v153
	v_mul_f32_e32 v153, v119, v218
	v_exp_f32_e32 v153, v153
	v_rcp_f32_e32 v232, v151
	s_mov_b64 s[40:41], 0
	v_add_f32_e32 v151, 1.0, v153
	v_mul_f32_e32 v153, v120, v216
	v_rcp_f32_e32 v231, v151
	v_add_f32_e32 v151, 1.0, v229
	v_exp_f32_e32 v153, v153
	v_mul_f32_e32 v229, v116, v215
	v_exp_f32_e32 v229, v229
	v_rcp_f32_e32 v233, v151
	v_add_f32_e32 v151, 1.0, v153
	v_mul_f32_e32 v153, v121, v155
	v_rcp_f32_e32 v234, v151
	v_add_f32_e32 v151, 1.0, v229
	v_exp_f32_e32 v153, v153
	v_mul_f32_e32 v229, v117, v154
	v_exp_f32_e32 v229, v229
	v_rcp_f32_e32 v236, v151
	v_add_f32_e32 v151, 1.0, v153
	v_rcp_f32_e32 v235, v151
	v_add_f32_e32 v151, 1.0, v229
	v_rcp_f32_e32 v237, v151
	v_mul_f32_e32 v151, v110, v214
	v_exp_f32_e32 v151, v151
	v_mul_f32_e32 v153, v106, v213
	v_exp_f32_e32 v153, v153
	v_pk_mul_f32 v[230:231], v[118:119], v[230:231]
	v_pk_mul_f32 v[232:233], v[114:115], v[232:233]
	v_pk_mul_f32 v[234:235], v[120:121], v[234:235]
	v_pk_mul_f32 v[236:237], v[116:117], v[236:237]
	v_cvt_pk_bf16_f32 v230, v230, v231
	v_cvt_pk_bf16_f32 v231, v234, v235
	v_cvt_pk_bf16_f32 v232, v232, v233
	v_cvt_pk_bf16_f32 v233, v236, v237
	v_add_f32_e32 v151, 1.0, v151
	global_store_dwordx4 v[210:211], v[230:233], off offset:256 sc1
	v_mul_f32_e32 v229, v107, v209
	v_exp_f32_e32 v229, v229
	v_rcp_f32_e32 v230, v151
	v_add_f32_e32 v151, 1.0, v153
	v_mul_f32_e32 v153, v111, v212
	v_exp_f32_e32 v153, v153
	v_rcp_f32_e32 v232, v151
	v_or_b32_e32 v210, 16, v150
	v_ashrrev_i32_e32 v211, 31, v210
	v_add_f32_e32 v151, 1.0, v153
	v_mul_f32_e32 v153, v112, v208
	v_rcp_f32_e32 v231, v151
	v_add_f32_e32 v151, 1.0, v229
	v_exp_f32_e32 v153, v153
	v_mul_f32_e32 v229, v108, v207
	v_exp_f32_e32 v229, v229
	v_rcp_f32_e32 v233, v151
	v_add_f32_e32 v151, 1.0, v153
	v_mul_f32_e32 v153, v113, v206
	v_rcp_f32_e32 v234, v151
	v_add_f32_e32 v151, 1.0, v229
	v_exp_f32_e32 v153, v153
	v_mul_f32_e32 v229, v109, v205
	v_exp_f32_e32 v229, v229
	v_rcp_f32_e32 v236, v151
	v_add_f32_e32 v151, 1.0, v153
	v_rcp_f32_e32 v235, v151
	v_add_f32_e32 v151, 1.0, v229
	v_rcp_f32_e32 v237, v151
	v_mul_f32_e32 v151, v102, v204
	v_exp_f32_e32 v151, v151
	v_mul_f32_e32 v153, v98, v203
	v_exp_f32_e32 v153, v153
	v_lshlrev_b64 v[210:211], s29, v[210:211]
	v_pk_mul_f32 v[230:231], v[110:111], v[230:231]
	v_pk_mul_f32 v[232:233], v[106:107], v[232:233]
	v_pk_mul_f32 v[234:235], v[112:113], v[234:235]
	v_pk_mul_f32 v[236:237], v[108:109], v[236:237]
	v_lshl_add_u64 v[210:211], v[210:211], 1, v[148:149]
	v_cvt_pk_bf16_f32 v230, v230, v231
	v_cvt_pk_bf16_f32 v231, v234, v235
	v_cvt_pk_bf16_f32 v232, v232, v233
	v_cvt_pk_bf16_f32 v233, v236, v237
	v_add_f32_e32 v151, 1.0, v151
	global_store_dwordx4 v[210:211], v[230:233], off sc1
	v_mul_f32_e32 v229, v99, v201
	v_exp_f32_e32 v229, v229
	v_rcp_f32_e32 v230, v151
	v_add_f32_e32 v151, 1.0, v153
	v_mul_f32_e32 v153, v103, v202
	v_exp_f32_e32 v153, v153
	v_rcp_f32_e32 v232, v151
	v_add_f32_e32 v151, 1.0, v153
	v_mul_f32_e32 v153, v104, v200
	v_rcp_f32_e32 v231, v151
	v_add_f32_e32 v151, 1.0, v229
	v_exp_f32_e32 v153, v153
	v_mul_f32_e32 v229, v100, v199
	v_exp_f32_e32 v229, v229
	v_rcp_f32_e32 v233, v151
	v_add_f32_e32 v151, 1.0, v153
	v_mul_f32_e32 v153, v105, v198
	v_rcp_f32_e32 v234, v151
	v_add_f32_e32 v151, 1.0, v229
	v_exp_f32_e32 v153, v153
	v_mul_f32_e32 v229, v101, v197
	v_exp_f32_e32 v229, v229
	v_rcp_f32_e32 v236, v151
	v_add_f32_e32 v151, 1.0, v153
	v_rcp_f32_e32 v235, v151
	v_add_f32_e32 v151, 1.0, v229
	v_rcp_f32_e32 v237, v151
	v_mul_f32_e32 v151, v94, v196
	v_exp_f32_e32 v151, v151
	v_mul_f32_e32 v153, v90, v195
	v_exp_f32_e32 v153, v153
	v_pk_mul_f32 v[230:231], v[102:103], v[230:231]
	v_pk_mul_f32 v[232:233], v[98:99], v[232:233]
	v_pk_mul_f32 v[234:235], v[104:105], v[234:235]
	v_pk_mul_f32 v[236:237], v[100:101], v[236:237]
	v_cvt_pk_bf16_f32 v230, v230, v231
	v_cvt_pk_bf16_f32 v231, v234, v235
	v_cvt_pk_bf16_f32 v232, v232, v233
	v_cvt_pk_bf16_f32 v233, v236, v237
	v_add_f32_e32 v151, 1.0, v151
	global_store_dwordx4 v[210:211], v[230:233], off offset:256 sc1
	v_mul_f32_e32 v229, v91, v193
	v_exp_f32_e32 v229, v229
	v_rcp_f32_e32 v230, v151
	v_add_f32_e32 v151, 1.0, v153
	v_mul_f32_e32 v153, v95, v194
	v_exp_f32_e32 v153, v153
	v_rcp_f32_e32 v232, v151
	v_or_b32_e32 v210, 32, v150
	v_ashrrev_i32_e32 v211, 31, v210
	v_add_f32_e32 v151, 1.0, v153
	v_mul_f32_e32 v153, v96, v192
	v_rcp_f32_e32 v231, v151
	v_add_f32_e32 v151, 1.0, v229
	v_exp_f32_e32 v153, v153
	v_mul_f32_e32 v229, v92, v191
	v_exp_f32_e32 v229, v229
	v_rcp_f32_e32 v233, v151
	v_add_f32_e32 v151, 1.0, v153
	v_mul_f32_e32 v153, v97, v190
	v_rcp_f32_e32 v234, v151
	v_add_f32_e32 v151, 1.0, v229
	v_exp_f32_e32 v153, v153
	v_mul_f32_e32 v229, v93, v189
	v_exp_f32_e32 v229, v229
	v_rcp_f32_e32 v236, v151
	v_add_f32_e32 v151, 1.0, v153
	v_rcp_f32_e32 v235, v151
	v_add_f32_e32 v151, 1.0, v229
	v_rcp_f32_e32 v237, v151
	v_mul_f32_e32 v151, v86, v188
	v_exp_f32_e32 v151, v151
	v_mul_f32_e32 v153, v82, v187
	v_exp_f32_e32 v153, v153
	v_lshlrev_b64 v[210:211], s29, v[210:211]
	v_pk_mul_f32 v[230:231], v[94:95], v[230:231]
	v_pk_mul_f32 v[232:233], v[90:91], v[232:233]
	v_pk_mul_f32 v[234:235], v[96:97], v[234:235]
	v_pk_mul_f32 v[236:237], v[92:93], v[236:237]
	v_lshl_add_u64 v[210:211], v[210:211], 1, v[148:149]
	v_cvt_pk_bf16_f32 v230, v230, v231
	v_cvt_pk_bf16_f32 v231, v234, v235
	v_cvt_pk_bf16_f32 v232, v232, v233
	v_cvt_pk_bf16_f32 v233, v236, v237
	v_add_f32_e32 v151, 1.0, v151
	global_store_dwordx4 v[210:211], v[230:233], off sc1
	v_mul_f32_e32 v229, v83, v185
	v_exp_f32_e32 v229, v229
	v_rcp_f32_e32 v230, v151
	v_add_f32_e32 v151, 1.0, v153
	v_mul_f32_e32 v153, v87, v186
	v_exp_f32_e32 v153, v153
	v_rcp_f32_e32 v232, v151
	v_add_f32_e32 v151, 1.0, v153
	v_mul_f32_e32 v153, v88, v184
	v_rcp_f32_e32 v231, v151
	v_add_f32_e32 v151, 1.0, v229
	v_exp_f32_e32 v153, v153
	v_mul_f32_e32 v229, v84, v183
	v_exp_f32_e32 v229, v229
	v_rcp_f32_e32 v233, v151
	v_add_f32_e32 v151, 1.0, v153
	v_mul_f32_e32 v153, v89, v182
	v_rcp_f32_e32 v234, v151
	v_add_f32_e32 v151, 1.0, v229
	v_exp_f32_e32 v153, v153
	v_mul_f32_e32 v229, v85, v181
	v_exp_f32_e32 v229, v229
	v_rcp_f32_e32 v236, v151
	v_add_f32_e32 v151, 1.0, v153
	v_rcp_f32_e32 v235, v151
	v_add_f32_e32 v151, 1.0, v229
	v_rcp_f32_e32 v237, v151
	v_fmamk_f32 v151, v180, 0xbdd2d3e8, v162
	v_mul_f32_e32 v151, v78, v151
	v_fmamk_f32 v153, v179, 0xbdd2d3e8, v162
	v_exp_f32_e32 v151, v151
	v_mul_f32_e32 v153, v74, v153
	v_exp_f32_e32 v153, v153
	v_pk_mul_f32 v[230:231], v[86:87], v[230:231]
	v_pk_mul_f32 v[232:233], v[82:83], v[232:233]
	v_pk_mul_f32 v[234:235], v[88:89], v[234:235]
	v_pk_mul_f32 v[236:237], v[84:85], v[236:237]
	v_cvt_pk_bf16_f32 v230, v230, v231
	v_cvt_pk_bf16_f32 v231, v234, v235
	v_cvt_pk_bf16_f32 v232, v232, v233
	v_cvt_pk_bf16_f32 v233, v236, v237
	v_add_f32_e32 v151, 1.0, v151
	global_store_dwordx4 v[210:211], v[230:233], off offset:256 sc1
	v_fmamk_f32 v229, v177, 0xbdd2d3e8, v162
	v_mul_f32_e32 v229, v75, v229
	v_rcp_f32_e32 v230, v151
	v_add_f32_e32 v151, 1.0, v153
	v_fmamk_f32 v153, v178, 0xbdd2d3e8, v162
	v_mul_f32_e32 v153, v79, v153
	v_exp_f32_e32 v153, v153
	v_exp_f32_e32 v229, v229
	v_rcp_f32_e32 v232, v151
	v_or_b32_e32 v210, 48, v150
	v_add_f32_e32 v151, 1.0, v153
	v_fmamk_f32 v153, v176, 0xbdd2d3e8, v162
	v_rcp_f32_e32 v231, v151
	v_add_f32_e32 v151, 1.0, v229
	v_mul_f32_e32 v153, v80, v153
	v_fmamk_f32 v229, v175, 0xbdd2d3e8, v162
	v_exp_f32_e32 v153, v153
	v_mul_f32_e32 v229, v76, v229
	v_exp_f32_e32 v229, v229
	v_rcp_f32_e32 v233, v151
	v_add_f32_e32 v151, 1.0, v153
	v_fmamk_f32 v153, v174, 0xbdd2d3e8, v162
	v_rcp_f32_e32 v234, v151
	v_add_f32_e32 v151, 1.0, v229
	v_mul_f32_e32 v153, v81, v153
	v_fmamk_f32 v229, v173, 0xbdd2d3e8, v162
	v_exp_f32_e32 v153, v153
	v_mul_f32_e32 v229, v77, v229
	v_exp_f32_e32 v229, v229
	v_rcp_f32_e32 v236, v151
	v_add_f32_e32 v151, 1.0, v153
	v_rcp_f32_e32 v235, v151
	v_add_f32_e32 v151, 1.0, v229
	v_rcp_f32_e32 v237, v151
	v_fmamk_f32 v151, v172, 0xbdd2d3e8, v162
	v_mul_f32_e32 v151, v70, v151
	v_fmamk_f32 v153, v171, 0xbdd2d3e8, v162
	v_exp_f32_e32 v151, v151
	v_mul_f32_e32 v153, v66, v153
	v_exp_f32_e32 v153, v153
	v_ashrrev_i32_e32 v211, 31, v210
	v_lshlrev_b64 v[210:211], s29, v[210:211]
	v_pk_mul_f32 v[230:231], v[78:79], v[230:231]
	v_pk_mul_f32 v[232:233], v[74:75], v[232:233]
	v_pk_mul_f32 v[234:235], v[80:81], v[234:235]
	v_pk_mul_f32 v[236:237], v[76:77], v[236:237]
	v_lshl_add_u64 v[210:211], v[210:211], 1, v[148:149]
	v_cvt_pk_bf16_f32 v230, v230, v231
	v_cvt_pk_bf16_f32 v231, v234, v235
	v_cvt_pk_bf16_f32 v232, v232, v233
	v_cvt_pk_bf16_f32 v233, v236, v237
	v_add_f32_e32 v151, 1.0, v151
	global_store_dwordx4 v[210:211], v[230:233], off sc1
	v_fmamk_f32 v229, v169, 0xbdd2d3e8, v162
	v_mul_f32_e32 v229, v67, v229
	v_rcp_f32_e32 v230, v151
	v_add_f32_e32 v151, 1.0, v153
	v_fmamk_f32 v153, v170, 0xbdd2d3e8, v162
	v_mul_f32_e32 v153, v71, v153
	v_exp_f32_e32 v153, v153
	v_exp_f32_e32 v229, v229
	v_rcp_f32_e32 v232, v151
	v_add_f32_e32 v151, 1.0, v153
	v_fmamk_f32 v153, v168, 0xbdd2d3e8, v162
	v_rcp_f32_e32 v231, v151
	v_add_f32_e32 v151, 1.0, v229
	v_mul_f32_e32 v153, v72, v153
	v_fmamk_f32 v229, v167, 0xbdd2d3e8, v162
	v_exp_f32_e32 v153, v153
	v_mul_f32_e32 v229, v68, v229
	v_exp_f32_e32 v229, v229
	v_rcp_f32_e32 v233, v151
	v_add_f32_e32 v151, 1.0, v153
	v_fmamk_f32 v153, v166, 0xbdd2d3e8, v162
	v_rcp_f32_e32 v234, v151
	v_add_f32_e32 v151, 1.0, v229
	v_mul_f32_e32 v153, v73, v153
	v_fmamk_f32 v229, v165, 0xbdd2d3e8, v162
	v_exp_f32_e32 v153, v153
	v_mul_f32_e32 v229, v69, v229
	v_exp_f32_e32 v229, v229
	v_rcp_f32_e32 v236, v151
	v_add_f32_e32 v151, 1.0, v153
	v_rcp_f32_e32 v235, v151
	v_add_f32_e32 v151, 1.0, v229
	v_rcp_f32_e32 v237, v151
	v_pk_mul_f32 v[230:231], v[70:71], v[230:231]
	v_pk_mul_f32 v[232:233], v[66:67], v[232:233]
	v_pk_mul_f32 v[234:235], v[72:73], v[234:235]
	v_pk_mul_f32 v[236:237], v[68:69], v[236:237]
	v_cvt_pk_bf16_f32 v230, v230, v231
	v_cvt_pk_bf16_f32 v231, v234, v235
	v_cvt_pk_bf16_f32 v232, v232, v233
	v_cvt_pk_bf16_f32 v233, v236, v237
	v_ashrrev_i32_e32 v153, 31, v152
	v_fmamk_f32 v151, v164, 0xbdd2d3e8, v162
	global_store_dwordx4 v[210:211], v[230:233], off offset:256 sc1
	v_lshlrev_b64 v[210:211], s29, v[152:153]
	v_mul_f32_e32 v151, v62, v151
	v_fmamk_f32 v153, v138, 0xbdd2d3e8, v162
	v_exp_f32_e32 v151, v151
	v_mul_f32_e32 v153, v58, v153
	v_exp_f32_e32 v153, v153
	v_mul_f32_e32 v229, v59, v59
	v_add_f32_e32 v151, 1.0, v151
	v_rcp_f32_e32 v230, v151
	v_add_f32_e32 v151, 1.0, v153
	v_mul_f32_e32 v153, v63, v63
	v_fmamk_f32 v153, v153, 0xbdd2d3e8, v162
	v_mul_f32_e32 v153, v63, v153
	v_fmamk_f32 v229, v229, 0xbdd2d3e8, v162
	v_exp_f32_e32 v153, v153
	v_mul_f32_e32 v229, v59, v229
	v_exp_f32_e32 v229, v229
	v_rcp_f32_e32 v232, v151
	v_add_f32_e32 v151, 1.0, v153
	v_mul_f32_e32 v153, v64, v64
	v_rcp_f32_e32 v231, v151
	v_add_f32_e32 v151, 1.0, v229
	v_fmamk_f32 v153, v153, 0xbdd2d3e8, v162
	v_mul_f32_e32 v229, v60, v60
	v_mul_f32_e32 v153, v64, v153
	v_fmamk_f32 v229, v229, 0xbdd2d3e8, v162
	v_exp_f32_e32 v153, v153
	v_mul_f32_e32 v229, v60, v229
	v_exp_f32_e32 v229, v229
	v_rcp_f32_e32 v233, v151
	v_add_f32_e32 v151, 1.0, v153
	v_mul_f32_e32 v153, v65, v65
	v_rcp_f32_e32 v234, v151
	v_add_f32_e32 v151, 1.0, v229
	v_fmamk_f32 v153, v153, 0xbdd2d3e8, v162
	v_mul_f32_e32 v229, v61, v61
	v_mul_f32_e32 v153, v65, v153
	v_fmamk_f32 v229, v229, 0xbdd2d3e8, v162
	v_exp_f32_e32 v153, v153
	v_mul_f32_e32 v229, v61, v229
	v_exp_f32_e32 v229, v229
	v_rcp_f32_e32 v236, v151
	v_add_f32_e32 v151, 1.0, v153
	v_rcp_f32_e32 v235, v151
	v_add_f32_e32 v151, 1.0, v229
	v_rcp_f32_e32 v237, v151
	v_mul_f32_e32 v151, v54, v54
	v_fmamk_f32 v151, v151, 0xbdd2d3e8, v162
	v_mul_f32_e32 v153, v50, v50
	v_mul_f32_e32 v151, v54, v151
	v_fmamk_f32 v153, v153, 0xbdd2d3e8, v162
	v_exp_f32_e32 v151, v151
	v_mul_f32_e32 v153, v50, v153
	v_exp_f32_e32 v153, v153
	v_pk_mul_f32 v[230:231], v[62:63], v[230:231]
	v_pk_mul_f32 v[232:233], v[58:59], v[232:233]
	v_pk_mul_f32 v[234:235], v[64:65], v[234:235]
	v_pk_mul_f32 v[236:237], v[60:61], v[236:237]
	v_lshl_add_u64 v[210:211], v[210:211], 1, v[148:149]
	v_cvt_pk_bf16_f32 v230, v230, v231
	v_cvt_pk_bf16_f32 v231, v234, v235
	v_cvt_pk_bf16_f32 v232, v232, v233
	v_cvt_pk_bf16_f32 v233, v236, v237
	v_add_f32_e32 v151, 1.0, v151
	global_store_dwordx4 v[210:211], v[230:233], off sc1
	v_mul_f32_e32 v229, v51, v51
	v_fmamk_f32 v229, v229, 0xbdd2d3e8, v162
	v_rcp_f32_e32 v230, v151
	v_add_f32_e32 v151, 1.0, v153
	v_mul_f32_e32 v153, v55, v55
	v_fmamk_f32 v153, v153, 0xbdd2d3e8, v162
	v_mul_f32_e32 v153, v55, v153
	v_exp_f32_e32 v153, v153
	v_mul_f32_e32 v229, v51, v229
	v_exp_f32_e32 v229, v229
	v_rcp_f32_e32 v232, v151
	v_add_f32_e32 v151, 1.0, v153
	v_mul_f32_e32 v153, v56, v56
	v_rcp_f32_e32 v231, v151
	v_add_f32_e32 v151, 1.0, v229
	v_fmamk_f32 v153, v153, 0xbdd2d3e8, v162
	v_mul_f32_e32 v229, v52, v52
	v_mul_f32_e32 v153, v56, v153
	v_fmamk_f32 v229, v229, 0xbdd2d3e8, v162
	v_exp_f32_e32 v153, v153
	v_mul_f32_e32 v229, v52, v229
	v_exp_f32_e32 v229, v229
	v_rcp_f32_e32 v233, v151
	v_add_f32_e32 v151, 1.0, v153
	v_mul_f32_e32 v153, v57, v57
	v_rcp_f32_e32 v234, v151
	v_add_f32_e32 v151, 1.0, v229
	v_fmamk_f32 v153, v153, 0xbdd2d3e8, v162
	v_mul_f32_e32 v229, v53, v53
	v_mul_f32_e32 v153, v57, v153
	v_fmamk_f32 v229, v229, 0xbdd2d3e8, v162
	v_exp_f32_e32 v153, v153
	v_mul_f32_e32 v229, v53, v229
	v_exp_f32_e32 v229, v229
	v_rcp_f32_e32 v236, v151
	v_add_f32_e32 v151, 1.0, v153
	v_rcp_f32_e32 v235, v151
	v_add_f32_e32 v151, 1.0, v229
	v_rcp_f32_e32 v237, v151
	v_mul_f32_e32 v151, v46, v46
	v_fmamk_f32 v151, v151, 0xbdd2d3e8, v162
	v_mul_f32_e32 v153, v42, v42
	v_mul_f32_e32 v151, v46, v151
	v_fmamk_f32 v153, v153, 0xbdd2d3e8, v162
	v_exp_f32_e32 v151, v151
	v_mul_f32_e32 v153, v42, v153
	v_exp_f32_e32 v153, v153
	v_pk_mul_f32 v[230:231], v[54:55], v[230:231]
	v_pk_mul_f32 v[232:233], v[50:51], v[232:233]
	v_pk_mul_f32 v[234:235], v[56:57], v[234:235]
	v_pk_mul_f32 v[236:237], v[52:53], v[236:237]
	v_cvt_pk_bf16_f32 v230, v230, v231
	v_cvt_pk_bf16_f32 v231, v234, v235
	v_cvt_pk_bf16_f32 v232, v232, v233
	v_cvt_pk_bf16_f32 v233, v236, v237
	v_add_f32_e32 v151, 1.0, v151
	global_store_dwordx4 v[210:211], v[230:233], off offset:256 sc1
	v_mul_f32_e32 v229, v43, v43
	v_fmamk_f32 v229, v229, 0xbdd2d3e8, v162
	v_rcp_f32_e32 v230, v151
	v_add_f32_e32 v151, 1.0, v153
	v_mul_f32_e32 v153, v47, v47
	v_fmamk_f32 v153, v153, 0xbdd2d3e8, v162
	v_mul_f32_e32 v153, v47, v153
	v_exp_f32_e32 v153, v153
	v_mul_f32_e32 v229, v43, v229
	v_exp_f32_e32 v229, v229
	v_rcp_f32_e32 v232, v151
	v_add_f32_e32 v151, 1.0, v153
	v_mul_f32_e32 v153, v48, v48
	v_rcp_f32_e32 v231, v151
	v_add_f32_e32 v151, 1.0, v229
	v_fmamk_f32 v153, v153, 0xbdd2d3e8, v162
	v_mul_f32_e32 v229, v44, v44
	v_mul_f32_e32 v153, v48, v153
	v_fmamk_f32 v229, v229, 0xbdd2d3e8, v162
	v_exp_f32_e32 v153, v153
	v_mul_f32_e32 v229, v44, v229
	v_exp_f32_e32 v229, v229
	v_rcp_f32_e32 v233, v151
	v_add_f32_e32 v151, 1.0, v153
	v_mul_f32_e32 v153, v49, v49
	v_rcp_f32_e32 v234, v151
	v_add_f32_e32 v151, 1.0, v229
	v_fmamk_f32 v153, v153, 0xbdd2d3e8, v162
	v_mul_f32_e32 v229, v45, v45
	v_mul_f32_e32 v153, v49, v153
	v_fmamk_f32 v229, v229, 0xbdd2d3e8, v162
	v_exp_f32_e32 v153, v153
	v_mul_f32_e32 v229, v45, v229
	v_exp_f32_e32 v229, v229
	v_rcp_f32_e32 v236, v151
	v_add_f32_e32 v151, 1.0, v153
	v_rcp_f32_e32 v235, v151
	v_add_f32_e32 v151, 1.0, v229
	v_rcp_f32_e32 v237, v151
	v_mul_f32_e32 v151, v38, v38
	v_fmamk_f32 v151, v151, 0xbdd2d3e8, v162
	v_mul_f32_e32 v153, v34, v34
	v_mul_f32_e32 v151, v38, v151
	v_fmamk_f32 v153, v153, 0xbdd2d3e8, v162
	v_exp_f32_e32 v151, v151
	v_mul_f32_e32 v153, v34, v153
	v_add_u32_e32 v210, 0x90, v150
	v_exp_f32_e32 v153, v153
	v_ashrrev_i32_e32 v211, 31, v210
	v_lshlrev_b64 v[210:211], s29, v[210:211]
	v_pk_mul_f32 v[230:231], v[46:47], v[230:231]
	v_pk_mul_f32 v[232:233], v[42:43], v[232:233]
	v_pk_mul_f32 v[234:235], v[48:49], v[234:235]
	v_pk_mul_f32 v[236:237], v[44:45], v[236:237]
	v_lshl_add_u64 v[210:211], v[210:211], 1, v[148:149]
	v_cvt_pk_bf16_f32 v230, v230, v231
	v_cvt_pk_bf16_f32 v231, v234, v235
	v_cvt_pk_bf16_f32 v232, v232, v233
	v_cvt_pk_bf16_f32 v233, v236, v237
	v_add_f32_e32 v151, 1.0, v151
	global_store_dwordx4 v[210:211], v[230:233], off sc1
	v_mul_f32_e32 v229, v35, v35
	v_fmamk_f32 v229, v229, 0xbdd2d3e8, v162
	v_rcp_f32_e32 v230, v151
	v_add_f32_e32 v151, 1.0, v153
	v_mul_f32_e32 v153, v39, v39
	v_fmamk_f32 v153, v153, 0xbdd2d3e8, v162
	v_mul_f32_e32 v153, v39, v153
	v_exp_f32_e32 v153, v153
	v_mul_f32_e32 v229, v35, v229
	v_exp_f32_e32 v229, v229
	v_rcp_f32_e32 v232, v151
	v_add_f32_e32 v151, 1.0, v153
	v_mul_f32_e32 v153, v40, v40
	v_rcp_f32_e32 v231, v151
	v_add_f32_e32 v151, 1.0, v229
	v_fmamk_f32 v153, v153, 0xbdd2d3e8, v162
	v_mul_f32_e32 v229, v36, v36
	v_mul_f32_e32 v153, v40, v153
	v_fmamk_f32 v229, v229, 0xbdd2d3e8, v162
	v_exp_f32_e32 v153, v153
	v_mul_f32_e32 v229, v36, v229
	v_exp_f32_e32 v229, v229
	v_rcp_f32_e32 v233, v151
	v_add_f32_e32 v151, 1.0, v153
	v_mul_f32_e32 v153, v41, v41
	v_rcp_f32_e32 v234, v151
	v_add_f32_e32 v151, 1.0, v229
	v_fmamk_f32 v153, v153, 0xbdd2d3e8, v162
	v_mul_f32_e32 v229, v37, v37
	v_mul_f32_e32 v153, v41, v153
	v_fmamk_f32 v229, v229, 0xbdd2d3e8, v162
	v_exp_f32_e32 v153, v153
	v_mul_f32_e32 v229, v37, v229
	v_exp_f32_e32 v229, v229
	v_rcp_f32_e32 v236, v151
	v_add_f32_e32 v151, 1.0, v153
	v_rcp_f32_e32 v235, v151
	v_add_f32_e32 v151, 1.0, v229
	v_rcp_f32_e32 v237, v151
	v_mul_f32_e32 v151, v30, v30
	v_fmamk_f32 v151, v151, 0xbdd2d3e8, v162
	v_mul_f32_e32 v153, v26, v26
	v_mul_f32_e32 v151, v30, v151
	v_fmamk_f32 v153, v153, 0xbdd2d3e8, v162
	v_exp_f32_e32 v151, v151
	v_mul_f32_e32 v153, v26, v153
	v_exp_f32_e32 v153, v153
	v_pk_mul_f32 v[230:231], v[38:39], v[230:231]
	v_pk_mul_f32 v[232:233], v[34:35], v[232:233]
	v_pk_mul_f32 v[234:235], v[40:41], v[234:235]
	v_pk_mul_f32 v[236:237], v[36:37], v[236:237]
	v_cvt_pk_bf16_f32 v230, v230, v231
	v_cvt_pk_bf16_f32 v231, v234, v235
	v_cvt_pk_bf16_f32 v232, v232, v233
	v_cvt_pk_bf16_f32 v233, v236, v237
	v_add_f32_e32 v151, 1.0, v151
	global_store_dwordx4 v[210:211], v[230:233], off offset:256 sc1
	v_mul_f32_e32 v229, v27, v27
	v_fmamk_f32 v229, v229, 0xbdd2d3e8, v162
	v_rcp_f32_e32 v230, v151
	v_add_f32_e32 v151, 1.0, v153
	v_mul_f32_e32 v153, v31, v31
	v_fmamk_f32 v153, v153, 0xbdd2d3e8, v162
	v_mul_f32_e32 v153, v31, v153
	v_exp_f32_e32 v153, v153
	v_mul_f32_e32 v229, v27, v229
	v_exp_f32_e32 v229, v229
	v_rcp_f32_e32 v232, v151
	v_add_f32_e32 v151, 1.0, v153
	v_mul_f32_e32 v153, v32, v32
	v_rcp_f32_e32 v231, v151
	v_add_f32_e32 v151, 1.0, v229
	v_fmamk_f32 v153, v153, 0xbdd2d3e8, v162
	v_mul_f32_e32 v229, v28, v28
	v_mul_f32_e32 v153, v32, v153
	v_fmamk_f32 v229, v229, 0xbdd2d3e8, v162
	v_exp_f32_e32 v153, v153
	v_mul_f32_e32 v229, v28, v229
	v_exp_f32_e32 v229, v229
	v_rcp_f32_e32 v233, v151
	v_add_f32_e32 v151, 1.0, v153
	v_mul_f32_e32 v153, v33, v33
	v_rcp_f32_e32 v234, v151
	v_add_f32_e32 v151, 1.0, v229
	v_fmamk_f32 v153, v153, 0xbdd2d3e8, v162
	v_mul_f32_e32 v229, v29, v29
	v_mul_f32_e32 v153, v33, v153
	v_fmamk_f32 v229, v229, 0xbdd2d3e8, v162
	v_exp_f32_e32 v153, v153
	v_mul_f32_e32 v229, v29, v229
	v_exp_f32_e32 v229, v229
	v_rcp_f32_e32 v236, v151
	v_add_f32_e32 v151, 1.0, v153
	v_rcp_f32_e32 v235, v151
	v_add_f32_e32 v151, 1.0, v229
	v_rcp_f32_e32 v237, v151
	v_mul_f32_e32 v151, v22, v22
	v_fmamk_f32 v151, v151, 0xbdd2d3e8, v162
	v_mul_f32_e32 v153, v18, v18
	v_mul_f32_e32 v151, v22, v151
	v_fmamk_f32 v153, v153, 0xbdd2d3e8, v162
	v_exp_f32_e32 v151, v151
	v_mul_f32_e32 v153, v18, v153
	v_add_u32_e32 v210, 0xa0, v150
	v_exp_f32_e32 v153, v153
	v_ashrrev_i32_e32 v211, 31, v210
	v_lshlrev_b64 v[210:211], s29, v[210:211]
	v_pk_mul_f32 v[230:231], v[30:31], v[230:231]
	v_pk_mul_f32 v[232:233], v[26:27], v[232:233]
	v_pk_mul_f32 v[234:235], v[32:33], v[234:235]
	v_pk_mul_f32 v[236:237], v[28:29], v[236:237]
	v_lshl_add_u64 v[210:211], v[210:211], 1, v[148:149]
	v_cvt_pk_bf16_f32 v230, v230, v231
	v_cvt_pk_bf16_f32 v231, v234, v235
	v_cvt_pk_bf16_f32 v232, v232, v233
	v_cvt_pk_bf16_f32 v233, v236, v237
	v_add_f32_e32 v151, 1.0, v151
	global_store_dwordx4 v[210:211], v[230:233], off sc1
	v_mul_f32_e32 v229, v19, v19
	v_fmamk_f32 v229, v229, 0xbdd2d3e8, v162
	v_rcp_f32_e32 v230, v151
	v_add_f32_e32 v151, 1.0, v153
	v_mul_f32_e32 v153, v23, v23
	v_fmamk_f32 v153, v153, 0xbdd2d3e8, v162
	v_mul_f32_e32 v153, v23, v153
	v_exp_f32_e32 v153, v153
	v_mul_f32_e32 v229, v19, v229
	v_exp_f32_e32 v229, v229
	v_rcp_f32_e32 v232, v151
	v_add_f32_e32 v151, 1.0, v153
	v_mul_f32_e32 v153, v24, v24
	v_rcp_f32_e32 v231, v151
	v_add_f32_e32 v151, 1.0, v229
	v_fmamk_f32 v153, v153, 0xbdd2d3e8, v162
	v_mul_f32_e32 v229, v20, v20
	v_mul_f32_e32 v153, v24, v153
	v_fmamk_f32 v229, v229, 0xbdd2d3e8, v162
	v_exp_f32_e32 v153, v153
	v_mul_f32_e32 v229, v20, v229
	v_exp_f32_e32 v229, v229
	v_rcp_f32_e32 v233, v151
	v_add_f32_e32 v151, 1.0, v153
	v_mul_f32_e32 v153, v25, v25
	v_rcp_f32_e32 v234, v151
	v_add_f32_e32 v151, 1.0, v229
	v_fmamk_f32 v153, v153, 0xbdd2d3e8, v162
	v_mul_f32_e32 v229, v21, v21
	v_mul_f32_e32 v153, v25, v153
	v_fmamk_f32 v229, v229, 0xbdd2d3e8, v162
	v_exp_f32_e32 v153, v153
	v_mul_f32_e32 v229, v21, v229
	v_exp_f32_e32 v229, v229
	v_rcp_f32_e32 v236, v151
	v_add_f32_e32 v151, 1.0, v153
	v_rcp_f32_e32 v235, v151
	v_add_f32_e32 v151, 1.0, v229
	v_rcp_f32_e32 v237, v151
	v_mul_f32_e32 v151, v14, v14
	v_fmamk_f32 v151, v151, 0xbdd2d3e8, v162
	v_mul_f32_e32 v153, v10, v10
	v_mul_f32_e32 v151, v14, v151
	v_fmamk_f32 v153, v153, 0xbdd2d3e8, v162
	v_exp_f32_e32 v151, v151
	v_mul_f32_e32 v153, v10, v153
	v_exp_f32_e32 v153, v153
	v_pk_mul_f32 v[230:231], v[22:23], v[230:231]
	v_pk_mul_f32 v[232:233], v[18:19], v[232:233]
	v_pk_mul_f32 v[234:235], v[24:25], v[234:235]
	v_pk_mul_f32 v[236:237], v[20:21], v[236:237]
	v_cvt_pk_bf16_f32 v230, v230, v231
	v_cvt_pk_bf16_f32 v231, v234, v235
	v_cvt_pk_bf16_f32 v232, v232, v233
	v_cvt_pk_bf16_f32 v233, v236, v237
	v_add_f32_e32 v151, 1.0, v151
	global_store_dwordx4 v[210:211], v[230:233], off offset:256 sc1
	v_mul_f32_e32 v229, v11, v11
	v_fmamk_f32 v229, v229, 0xbdd2d3e8, v162
	v_rcp_f32_e32 v230, v151
	v_add_f32_e32 v151, 1.0, v153
	v_mul_f32_e32 v153, v15, v15
	v_fmamk_f32 v153, v153, 0xbdd2d3e8, v162
	v_mul_f32_e32 v153, v15, v153
	v_exp_f32_e32 v153, v153
	v_mul_f32_e32 v229, v11, v229
	v_exp_f32_e32 v229, v229
	v_rcp_f32_e32 v232, v151
	v_add_f32_e32 v151, 1.0, v153
	v_mul_f32_e32 v153, v16, v16
	v_rcp_f32_e32 v231, v151
	v_add_f32_e32 v151, 1.0, v229
	v_fmamk_f32 v153, v153, 0xbdd2d3e8, v162
	v_mul_f32_e32 v229, v12, v12
	v_mul_f32_e32 v153, v16, v153
	v_fmamk_f32 v229, v229, 0xbdd2d3e8, v162
	v_exp_f32_e32 v153, v153
	v_mul_f32_e32 v229, v12, v229
	v_exp_f32_e32 v229, v229
	v_rcp_f32_e32 v233, v151
	v_add_f32_e32 v151, 1.0, v153
	v_mul_f32_e32 v153, v17, v17
	v_rcp_f32_e32 v234, v151
	v_add_f32_e32 v151, 1.0, v229
	v_fmamk_f32 v153, v153, 0xbdd2d3e8, v162
	v_mul_f32_e32 v229, v13, v13
	v_mul_f32_e32 v153, v17, v153
	v_fmamk_f32 v229, v229, 0xbdd2d3e8, v162
	v_exp_f32_e32 v153, v153
	v_mul_f32_e32 v229, v13, v229
	v_exp_f32_e32 v229, v229
	v_rcp_f32_e32 v236, v151
	v_add_f32_e32 v151, 1.0, v153
	v_rcp_f32_e32 v235, v151
	v_add_f32_e32 v151, 1.0, v229
	v_rcp_f32_e32 v237, v151
	v_mul_f32_e32 v151, v6, v6
	v_fmamk_f32 v151, v151, 0xbdd2d3e8, v162
	v_mul_f32_e32 v153, v2, v2
	v_mul_f32_e32 v151, v6, v151
	v_fmamk_f32 v153, v153, 0xbdd2d3e8, v162
	v_exp_f32_e32 v151, v151
	v_mul_f32_e32 v153, v2, v153
	v_add_u32_e32 v210, 0xb0, v150
	v_exp_f32_e32 v153, v153
	v_ashrrev_i32_e32 v211, 31, v210
	v_lshlrev_b64 v[210:211], s29, v[210:211]
	v_pk_mul_f32 v[230:231], v[14:15], v[230:231]
	v_pk_mul_f32 v[232:233], v[10:11], v[232:233]
	v_pk_mul_f32 v[234:235], v[16:17], v[234:235]
	v_pk_mul_f32 v[236:237], v[12:13], v[236:237]
	v_lshl_add_u64 v[210:211], v[210:211], 1, v[148:149]
	v_cvt_pk_bf16_f32 v230, v230, v231
	v_cvt_pk_bf16_f32 v231, v234, v235
	v_cvt_pk_bf16_f32 v232, v232, v233
	v_cvt_pk_bf16_f32 v233, v236, v237
	v_add_f32_e32 v151, 1.0, v151
	global_store_dwordx4 v[210:211], v[230:233], off sc1
	v_mul_f32_e32 v229, v3, v3
	v_fmamk_f32 v229, v229, 0xbdd2d3e8, v162
	v_rcp_f32_e32 v230, v151
	v_add_f32_e32 v151, 1.0, v153
	v_mul_f32_e32 v153, v7, v7
	v_fmamk_f32 v153, v153, 0xbdd2d3e8, v162
	v_mul_f32_e32 v153, v7, v153
	v_exp_f32_e32 v153, v153
	v_mul_f32_e32 v229, v3, v229
	v_exp_f32_e32 v229, v229
	v_rcp_f32_e32 v232, v151
	v_add_f32_e32 v151, 1.0, v153
	v_mul_f32_e32 v153, v8, v8
	v_rcp_f32_e32 v231, v151
	v_add_f32_e32 v151, 1.0, v229
	v_fmamk_f32 v153, v153, 0xbdd2d3e8, v162
	v_mul_f32_e32 v229, v4, v4
	v_mul_f32_e32 v153, v8, v153
	v_fmamk_f32 v229, v229, 0xbdd2d3e8, v162
	v_exp_f32_e32 v153, v153
	v_mul_f32_e32 v229, v4, v229
	v_exp_f32_e32 v229, v229
	v_rcp_f32_e32 v233, v151
	v_add_f32_e32 v151, 1.0, v153
	v_mul_f32_e32 v153, v9, v9
	v_rcp_f32_e32 v234, v151
	v_add_f32_e32 v151, 1.0, v229
	v_fmamk_f32 v153, v153, 0xbdd2d3e8, v162
	v_mul_f32_e32 v229, v5, v5
	v_mul_f32_e32 v153, v9, v153
	v_fmamk_f32 v229, v229, 0xbdd2d3e8, v162
	v_exp_f32_e32 v153, v153
	v_mul_f32_e32 v229, v5, v229
	v_exp_f32_e32 v229, v229
	v_rcp_f32_e32 v236, v151
	v_add_f32_e32 v151, 1.0, v153
	v_rcp_f32_e32 v235, v151
	v_add_f32_e32 v151, 1.0, v229
	v_rcp_f32_e32 v237, v151
	v_pk_mul_f32 v[230:231], v[6:7], v[230:231]
	v_pk_mul_f32 v[232:233], v[2:3], v[232:233]
	v_pk_mul_f32 v[234:235], v[8:9], v[234:235]
	v_pk_mul_f32 v[236:237], v[4:5], v[236:237]
	v_cvt_pk_bf16_f32 v230, v230, v231
	v_cvt_pk_bf16_f32 v231, v234, v235
	v_cvt_pk_bf16_f32 v232, v232, v233
	v_cvt_pk_bf16_f32 v233, v236, v237
	global_store_dwordx4 v[210:211], v[230:233], off offset:256 sc1
.LBB0_165:
	s_andn2_b64 vcc, exec, s[40:41]
	s_cbranch_vccnz .LBB0_183
	v_and_b32_e32 v153, 64, v163
	v_xor_b32_e32 v151, 16, v163
	v_add_u32_e32 v153, 64, v153
	v_cmp_lt_i32_e32 vcc, v151, v153
	v_mul_f32_e32 v227, v122, v227
	v_exp_f32_e32 v227, v227
	v_cndmask_b32_e32 v151, v163, v151, vcc
	v_lshlrev_b32_e32 v211, 2, v151
	v_xor_b32_e32 v151, 32, v163
	v_cmp_lt_i32_e32 vcc, v151, v153
	v_mul_f32_e32 v153, v126, v228
	v_exp_f32_e32 v153, v153
	v_cndmask_b32_e32 v151, v163, v151, vcc
	s_and_b64 s[38:39], s[38:39], exec
	v_lshlrev_b32_e32 v210, 2, v151
	v_ashrrev_i32_e32 v151, 31, v150
	s_cselect_b32 s29, 11, 10
	v_lshlrev_b64 v[230:231], s29, v[150:151]
	v_add_f32_e32 v153, 1.0, v153
	v_mul_f32_e32 v226, v127, v226
	v_lshl_add_u64 v[228:229], v[230:231], 1, v[148:149]
	v_rcp_f32_e32 v230, v153
	v_add_f32_e32 v153, 1.0, v227
	v_exp_f32_e32 v227, v226
	v_mul_f32_e32 v225, v123, v225
	v_exp_f32_e32 v225, v225
	v_mul_f32_e32 v224, v128, v224
	v_exp_f32_e32 v224, v224
	v_mul_f32_e32 v223, v124, v223
	v_exp_f32_e32 v223, v223
	v_rcp_f32_e32 v226, v153
	v_add_f32_e32 v153, 1.0, v227
	v_rcp_f32_e32 v231, v153
	v_add_f32_e32 v153, 1.0, v225
	v_rcp_f32_e32 v227, v153
	v_add_f32_e32 v153, 1.0, v224
	v_mul_f32_e32 v222, v129, v222
	v_rcp_f32_e32 v224, v153
	v_add_f32_e32 v153, 1.0, v223
	v_exp_f32_e32 v223, v222
	v_mul_f32_e32 v221, v125, v221
	v_exp_f32_e32 v221, v221
	v_rcp_f32_e32 v222, v153
	v_add_f32_e32 v153, 1.0, v223
	v_rcp_f32_e32 v225, v153
	v_add_f32_e32 v153, 1.0, v221
	v_rcp_f32_e32 v223, v153
	v_mul_f32_e32 v153, v118, v220
	v_exp_f32_e32 v153, v153
	v_mul_f32_e32 v219, v114, v219
	v_exp_f32_e32 v219, v219
	v_mul_f32_e32 v218, v119, v218
	v_add_f32_e32 v153, 1.0, v153
	v_rcp_f32_e32 v220, v153
	v_add_f32_e32 v153, 1.0, v219
	v_exp_f32_e32 v219, v218
	v_mul_f32_e32 v217, v115, v217
	v_exp_f32_e32 v217, v217
	v_mul_f32_e32 v216, v120, v216
	v_exp_f32_e32 v216, v216
	v_mul_f32_e32 v215, v116, v215
	v_exp_f32_e32 v215, v215
	v_rcp_f32_e32 v218, v153
	v_add_f32_e32 v153, 1.0, v219
	v_rcp_f32_e32 v221, v153
	v_add_f32_e32 v153, 1.0, v217
	v_mul_f32_e32 v155, v121, v155
	v_rcp_f32_e32 v219, v153
	v_add_f32_e32 v153, 1.0, v216
	v_exp_f32_e32 v155, v155
	v_mul_f32_e32 v154, v117, v154
	v_rcp_f32_e32 v216, v153
	v_add_f32_e32 v153, 1.0, v215
	v_exp_f32_e32 v215, v154
	v_rcp_f32_e32 v154, v153
	v_add_f32_e32 v153, 1.0, v155
	v_rcp_f32_e32 v217, v153
	v_add_f32_e32 v153, 1.0, v215
	v_pk_mul_f32 v[226:227], v[122:123], v[226:227]
	v_rcp_f32_e32 v155, v153
	v_pk_mul_f32 v[230:231], v[126:127], v[230:231]
	v_pk_mul_f32 v[232:233], v[124:125], v[222:223]
	v_pk_mul_f32 v[222:223], v[226:227], v[226:227]
	v_pk_mul_f32 v[224:225], v[128:129], v[224:225]
	v_pk_fma_f32 v[234:235], v[230:231], v[230:231], v[222:223]
	v_pk_mul_f32 v[222:223], v[232:233], v[232:233]
	v_pk_mul_f32 v[218:219], v[114:115], v[218:219]
	v_pk_fma_f32 v[236:237], v[224:225], v[224:225], v[222:223]
	v_add_f32_e32 v153, v234, v235
	v_pk_mul_f32 v[220:221], v[118:119], v[220:221]
	v_pk_mul_f32 v[238:239], v[116:117], v[154:155]
	v_pk_mul_f32 v[154:155], v[218:219], v[218:219]
	v_add_f32_e32 v153, v236, v153
	v_pk_fma_f32 v[154:155], v[220:221], v[220:221], v[154:155]
	v_add_f32_e32 v153, v237, v153
	v_cvt_pk_bf16_f32 v222, v230, v231
	v_pk_mul_f32 v[230:231], v[120:121], v[216:217]
	v_pk_mul_f32 v[216:217], v[238:239], v[238:239]
	v_add_f32_e32 v153, v153, v154
	v_pk_fma_f32 v[216:217], v[230:231], v[230:231], v[216:217]
	v_add_f32_e32 v153, v155, v153
	v_add_f32_e32 v153, v216, v153
	v_add_f32_e32 v153, v217, v153
	ds_bpermute_b32 v154, v211, v153
	v_cvt_pk_bf16_f32 v223, v224, v225
	v_cvt_pk_bf16_f32 v224, v226, v227
	v_cvt_pk_bf16_f32 v225, v232, v233
	v_cvt_pk_bf16_f32 v216, v220, v221
	s_waitcnt lgkmcnt(0)
	v_add_f32_e32 v153, v153, v154
	ds_bpermute_b32 v154, v210, v153
	v_cvt_pk_bf16_f32 v217, v230, v231
	v_cvt_pk_bf16_f32 v218, v218, v219
	v_cvt_pk_bf16_f32 v219, v238, v239
	global_store_dwordx4 v[228:229], v[222:225], off sc1
	global_store_dwordx4 v[228:229], v[216:219], off offset:256 sc1
	s_and_saveexec_b64 s[38:39], s[0:1]
	s_cbranch_execz .LBB0_168
	v_lshl_add_u64 v[216:217], v[150:151], 2, s[10:11]
	s_waitcnt lgkmcnt(0)
	v_add_f32_e32 v151, v153, v154
	global_atomic_add_f32 v[216:217], v151, off
.LBB0_168:
	s_or_b64 exec, exec, s[38:39]
	v_mul_f32_e32 v151, v110, v214
	v_exp_f32_e32 v151, v151
	v_mul_f32_e32 v153, v106, v213
	v_exp_f32_e32 v153, v153
	s_waitcnt lgkmcnt(0)
	v_or_b32_e32 v154, 16, v150
	v_ashrrev_i32_e32 v155, 31, v154
	v_lshlrev_b64 v[216:217], s29, v[154:155]
	v_add_f32_e32 v151, 1.0, v151
	v_lshl_add_u64 v[214:215], v[216:217], 1, v[148:149]
	v_rcp_f32_e32 v216, v151
	v_add_f32_e32 v151, 1.0, v153
	v_mul_f32_e32 v153, v111, v212
	v_exp_f32_e32 v153, v153
	v_mul_f32_e32 v209, v107, v209
	v_exp_f32_e32 v209, v209
	v_rcp_f32_e32 v212, v151
	v_add_f32_e32 v151, 1.0, v153
	v_mul_f32_e32 v153, v112, v208
	v_exp_f32_e32 v153, v153
	v_rcp_f32_e32 v217, v151
	v_add_f32_e32 v151, 1.0, v209
	v_mul_f32_e32 v207, v108, v207
	v_exp_f32_e32 v207, v207
	v_rcp_f32_e32 v213, v151
	v_add_f32_e32 v151, 1.0, v153
	v_mul_f32_e32 v153, v113, v206
	v_exp_f32_e32 v153, v153
	v_mul_f32_e32 v205, v109, v205
	v_exp_f32_e32 v205, v205
	v_rcp_f32_e32 v208, v151
	v_add_f32_e32 v151, 1.0, v207
	v_rcp_f32_e32 v206, v151
	v_add_f32_e32 v151, 1.0, v153
	v_rcp_f32_e32 v209, v151
	v_add_f32_e32 v151, 1.0, v205
	v_rcp_f32_e32 v207, v151
	v_mul_f32_e32 v151, v102, v204
	v_exp_f32_e32 v151, v151
	v_mul_f32_e32 v153, v98, v203
	v_exp_f32_e32 v153, v153
	v_mul_f32_e32 v201, v99, v201
	v_add_f32_e32 v151, 1.0, v151
	v_rcp_f32_e32 v204, v151
	v_add_f32_e32 v151, 1.0, v153
	v_mul_f32_e32 v153, v103, v202
	v_exp_f32_e32 v153, v153
	v_exp_f32_e32 v201, v201
	v_rcp_f32_e32 v202, v151
	v_mul_f32_e32 v199, v100, v199
	v_add_f32_e32 v151, 1.0, v153
	v_mul_f32_e32 v153, v104, v200
	v_exp_f32_e32 v153, v153
	v_rcp_f32_e32 v205, v151
	v_add_f32_e32 v151, 1.0, v201
	v_exp_f32_e32 v199, v199
	v_rcp_f32_e32 v203, v151
	v_add_f32_e32 v151, 1.0, v153
	v_mul_f32_e32 v153, v105, v198
	v_exp_f32_e32 v153, v153
	v_mul_f32_e32 v197, v101, v197
	v_exp_f32_e32 v197, v197
	v_rcp_f32_e32 v200, v151
	v_add_f32_e32 v151, 1.0, v199
	v_rcp_f32_e32 v198, v151
	v_add_f32_e32 v151, 1.0, v153
	v_rcp_f32_e32 v201, v151
	v_add_f32_e32 v151, 1.0, v197
	v_pk_mul_f32 v[212:213], v[106:107], v[212:213]
	v_rcp_f32_e32 v199, v151
	v_pk_mul_f32 v[216:217], v[110:111], v[216:217]
	v_pk_mul_f32 v[218:219], v[108:109], v[206:207]
	v_pk_mul_f32 v[206:207], v[212:213], v[212:213]
	v_pk_mul_f32 v[208:209], v[112:113], v[208:209]
	v_pk_fma_f32 v[220:221], v[216:217], v[216:217], v[206:207]
	v_pk_mul_f32 v[206:207], v[218:219], v[218:219]
	v_pk_mul_f32 v[202:203], v[98:99], v[202:203]
	v_pk_fma_f32 v[222:223], v[208:209], v[208:209], v[206:207]
	v_add_f32_e32 v151, v220, v221
	v_cvt_pk_bf16_f32 v206, v216, v217
	v_pk_mul_f32 v[204:205], v[102:103], v[204:205]
	v_pk_mul_f32 v[216:217], v[100:101], v[198:199]
	v_pk_mul_f32 v[198:199], v[202:203], v[202:203]
	v_add_f32_e32 v151, v222, v151
	v_pk_fma_f32 v[198:199], v[204:205], v[204:205], v[198:199]
	v_add_f32_e32 v151, v223, v151
	v_cvt_pk_bf16_f32 v207, v208, v209
	v_pk_mul_f32 v[200:201], v[104:105], v[200:201]
	v_pk_mul_f32 v[208:209], v[216:217], v[216:217]
	v_add_f32_e32 v151, v151, v198
	v_pk_fma_f32 v[208:209], v[200:201], v[200:201], v[208:209]
	v_add_f32_e32 v151, v199, v151
	v_add_f32_e32 v151, v208, v151
	v_add_f32_e32 v151, v209, v151
	ds_bpermute_b32 v153, v211, v151
	v_cvt_pk_bf16_f32 v208, v212, v213
	v_cvt_pk_bf16_f32 v209, v218, v219
	v_cvt_pk_bf16_f32 v198, v204, v205
	v_cvt_pk_bf16_f32 v199, v200, v201
	s_waitcnt lgkmcnt(0)
	v_add_f32_e32 v151, v151, v153
	ds_bpermute_b32 v153, v210, v151
	v_cvt_pk_bf16_f32 v200, v202, v203
	v_cvt_pk_bf16_f32 v201, v216, v217
	global_store_dwordx4 v[214:215], v[206:209], off sc1
	global_store_dwordx4 v[214:215], v[198:201], off offset:256 sc1
	s_and_saveexec_b64 s[38:39], s[0:1]
	s_cbranch_execz .LBB0_170
	v_lshl_add_u64 v[154:155], v[154:155], 2, s[10:11]
	s_waitcnt lgkmcnt(0)
	v_add_f32_e32 v151, v151, v153
	global_atomic_add_f32 v[154:155], v151, off
.LBB0_170:
	s_or_b64 exec, exec, s[38:39]
	v_mul_f32_e32 v151, v94, v196
	v_exp_f32_e32 v151, v151
	s_waitcnt lgkmcnt(0)
	v_mul_f32_e32 v153, v90, v195
	v_exp_f32_e32 v153, v153
	v_or_b32_e32 v154, 32, v150
	v_ashrrev_i32_e32 v155, 31, v154
	v_lshlrev_b64 v[198:199], s29, v[154:155]
	v_add_f32_e32 v151, 1.0, v151
	v_lshl_add_u64 v[196:197], v[198:199], 1, v[148:149]
	v_rcp_f32_e32 v198, v151
	v_add_f32_e32 v151, 1.0, v153
	v_mul_f32_e32 v153, v95, v194
	v_exp_f32_e32 v153, v153
	v_mul_f32_e32 v193, v91, v193
	v_exp_f32_e32 v193, v193
	v_rcp_f32_e32 v194, v151
	v_add_f32_e32 v151, 1.0, v153
	v_mul_f32_e32 v153, v96, v192
	v_exp_f32_e32 v153, v153
	v_rcp_f32_e32 v199, v151
	v_add_f32_e32 v151, 1.0, v193
	v_mul_f32_e32 v191, v92, v191
	v_exp_f32_e32 v191, v191
	v_rcp_f32_e32 v195, v151
	v_add_f32_e32 v151, 1.0, v153
	v_mul_f32_e32 v153, v97, v190
	v_exp_f32_e32 v153, v153
	v_mul_f32_e32 v189, v93, v189
	v_exp_f32_e32 v189, v189
	v_rcp_f32_e32 v192, v151
	v_add_f32_e32 v151, 1.0, v191
	v_rcp_f32_e32 v190, v151
	v_add_f32_e32 v151, 1.0, v153
	v_rcp_f32_e32 v193, v151
	v_add_f32_e32 v151, 1.0, v189
	v_rcp_f32_e32 v191, v151
	v_mul_f32_e32 v151, v86, v188
	v_exp_f32_e32 v151, v151
	v_mul_f32_e32 v153, v82, v187
	v_exp_f32_e32 v153, v153
	v_mul_f32_e32 v185, v83, v185
	v_add_f32_e32 v151, 1.0, v151
	v_rcp_f32_e32 v188, v151
	v_add_f32_e32 v151, 1.0, v153
	v_mul_f32_e32 v153, v87, v186
	v_exp_f32_e32 v153, v153
	v_exp_f32_e32 v185, v185
	v_rcp_f32_e32 v186, v151
	v_mul_f32_e32 v183, v84, v183
	v_add_f32_e32 v151, 1.0, v153
	v_mul_f32_e32 v153, v88, v184
	v_exp_f32_e32 v153, v153
	v_rcp_f32_e32 v189, v151
	v_add_f32_e32 v151, 1.0, v185
	v_exp_f32_e32 v183, v183
	v_rcp_f32_e32 v187, v151
	v_add_f32_e32 v151, 1.0, v153
	v_mul_f32_e32 v153, v89, v182
	v_exp_f32_e32 v153, v153
	v_mul_f32_e32 v181, v85, v181
	v_exp_f32_e32 v181, v181
	v_rcp_f32_e32 v184, v151
	v_add_f32_e32 v151, 1.0, v183
	v_rcp_f32_e32 v182, v151
	v_add_f32_e32 v151, 1.0, v153
	v_rcp_f32_e32 v185, v151
	v_add_f32_e32 v151, 1.0, v181
	v_pk_mul_f32 v[194:195], v[90:91], v[194:195]
	v_rcp_f32_e32 v183, v151
	v_pk_mul_f32 v[198:199], v[94:95], v[198:199]
	v_pk_mul_f32 v[200:201], v[92:93], v[190:191]
	v_pk_mul_f32 v[190:191], v[194:195], v[194:195]
	v_pk_mul_f32 v[192:193], v[96:97], v[192:193]
	v_pk_fma_f32 v[202:203], v[198:199], v[198:199], v[190:191]
	v_pk_mul_f32 v[190:191], v[200:201], v[200:201]
	v_pk_mul_f32 v[186:187], v[82:83], v[186:187]
	v_pk_fma_f32 v[204:205], v[192:193], v[192:193], v[190:191]
	v_add_f32_e32 v151, v202, v203
	v_cvt_pk_bf16_f32 v190, v198, v199
	v_pk_mul_f32 v[188:189], v[86:87], v[188:189]
	v_pk_mul_f32 v[198:199], v[84:85], v[182:183]
	v_pk_mul_f32 v[182:183], v[186:187], v[186:187]
	v_add_f32_e32 v151, v204, v151
	v_pk_fma_f32 v[182:183], v[188:189], v[188:189], v[182:183]
	v_add_f32_e32 v151, v205, v151
	v_cvt_pk_bf16_f32 v191, v192, v193
	v_pk_mul_f32 v[184:185], v[88:89], v[184:185]
	v_pk_mul_f32 v[192:193], v[198:199], v[198:199]
	v_add_f32_e32 v151, v151, v182
	v_pk_fma_f32 v[192:193], v[184:185], v[184:185], v[192:193]
	v_add_f32_e32 v151, v183, v151
	v_add_f32_e32 v151, v192, v151
	v_add_f32_e32 v151, v193, v151
	ds_bpermute_b32 v153, v211, v151
	v_cvt_pk_bf16_f32 v192, v194, v195
	v_cvt_pk_bf16_f32 v193, v200, v201
	v_cvt_pk_bf16_f32 v182, v188, v189
	v_cvt_pk_bf16_f32 v183, v184, v185
	s_waitcnt lgkmcnt(0)
	v_add_f32_e32 v151, v151, v153
	ds_bpermute_b32 v153, v210, v151
	v_cvt_pk_bf16_f32 v184, v186, v187
	v_cvt_pk_bf16_f32 v185, v198, v199
	global_store_dwordx4 v[196:197], v[190:193], off sc1
	global_store_dwordx4 v[196:197], v[182:185], off offset:256 sc1
	s_and_saveexec_b64 s[38:39], s[0:1]
	s_cbranch_execz .LBB0_172
	v_lshl_add_u64 v[154:155], v[154:155], 2, s[10:11]
	s_waitcnt lgkmcnt(0)
	v_add_f32_e32 v151, v151, v153
	global_atomic_add_f32 v[154:155], v151, off
.LBB0_172:
	s_or_b64 exec, exec, s[38:39]
	v_fmamk_f32 v151, v180, 0xbdd2d3e8, v162
	v_mul_f32_e32 v151, v78, v151
	s_waitcnt lgkmcnt(0)
	v_fmamk_f32 v153, v179, 0xbdd2d3e8, v162
	v_exp_f32_e32 v151, v151
	v_mul_f32_e32 v153, v74, v153
	v_exp_f32_e32 v153, v153
	v_or_b32_e32 v154, 48, v150
	v_ashrrev_i32_e32 v155, 31, v154
	v_lshlrev_b64 v[182:183], s29, v[154:155]
	v_add_f32_e32 v151, 1.0, v151
	v_lshl_add_u64 v[180:181], v[182:183], 1, v[148:149]
	v_rcp_f32_e32 v182, v151
	v_add_f32_e32 v151, 1.0, v153
	v_fmamk_f32 v153, v178, 0xbdd2d3e8, v162
	v_mul_f32_e32 v153, v79, v153
	v_exp_f32_e32 v153, v153
	v_fmamk_f32 v177, v177, 0xbdd2d3e8, v162
	v_mul_f32_e32 v177, v75, v177
	v_rcp_f32_e32 v178, v151
	v_add_f32_e32 v151, 1.0, v153
	v_fmamk_f32 v153, v176, 0xbdd2d3e8, v162
	v_exp_f32_e32 v177, v177
	v_mul_f32_e32 v153, v80, v153
	v_exp_f32_e32 v153, v153
	v_rcp_f32_e32 v183, v151
	v_add_f32_e32 v151, 1.0, v177
	v_fmamk_f32 v175, v175, 0xbdd2d3e8, v162
	v_mul_f32_e32 v175, v76, v175
	v_rcp_f32_e32 v179, v151
	v_add_f32_e32 v151, 1.0, v153
	v_fmamk_f32 v153, v174, 0xbdd2d3e8, v162
	v_exp_f32_e32 v175, v175
	v_mul_f32_e32 v153, v81, v153
	v_fmamk_f32 v173, v173, 0xbdd2d3e8, v162
	v_exp_f32_e32 v153, v153
	v_mul_f32_e32 v173, v77, v173
	v_exp_f32_e32 v173, v173
	v_rcp_f32_e32 v176, v151
	v_add_f32_e32 v151, 1.0, v175
	v_rcp_f32_e32 v174, v151
	v_add_f32_e32 v151, 1.0, v153
	v_rcp_f32_e32 v177, v151
	v_add_f32_e32 v151, 1.0, v173
	v_rcp_f32_e32 v175, v151
	v_fmamk_f32 v151, v172, 0xbdd2d3e8, v162
	v_mul_f32_e32 v151, v70, v151
	v_fmamk_f32 v153, v171, 0xbdd2d3e8, v162
	v_exp_f32_e32 v151, v151
	v_mul_f32_e32 v153, v66, v153
	v_exp_f32_e32 v153, v153
	v_fmamk_f32 v169, v169, 0xbdd2d3e8, v162
	v_add_f32_e32 v151, 1.0, v151
	v_rcp_f32_e32 v172, v151
	v_add_f32_e32 v151, 1.0, v153
	v_fmamk_f32 v153, v170, 0xbdd2d3e8, v162
	v_mul_f32_e32 v153, v71, v153
	v_exp_f32_e32 v153, v153
	v_mul_f32_e32 v169, v67, v169
	v_rcp_f32_e32 v170, v151
	v_exp_f32_e32 v169, v169
	v_add_f32_e32 v151, 1.0, v153
	v_fmamk_f32 v153, v168, 0xbdd2d3e8, v162
	v_mul_f32_e32 v153, v72, v153
	v_exp_f32_e32 v153, v153
	v_rcp_f32_e32 v173, v151
	v_add_f32_e32 v151, 1.0, v169
	v_fmamk_f32 v167, v167, 0xbdd2d3e8, v162
	v_mul_f32_e32 v167, v68, v167
	v_rcp_f32_e32 v171, v151
	v_add_f32_e32 v151, 1.0, v153
	v_fmamk_f32 v153, v166, 0xbdd2d3e8, v162
	v_exp_f32_e32 v167, v167
	v_mul_f32_e32 v153, v73, v153
	v_fmamk_f32 v165, v165, 0xbdd2d3e8, v162
	v_exp_f32_e32 v153, v153
	v_mul_f32_e32 v165, v69, v165
	v_exp_f32_e32 v165, v165
	v_rcp_f32_e32 v168, v151
	v_add_f32_e32 v151, 1.0, v167
	v_rcp_f32_e32 v166, v151
	v_add_f32_e32 v151, 1.0, v153
	v_rcp_f32_e32 v169, v151
	v_add_f32_e32 v151, 1.0, v165
	v_pk_mul_f32 v[178:179], v[74:75], v[178:179]
	v_rcp_f32_e32 v167, v151
	v_pk_mul_f32 v[182:183], v[78:79], v[182:183]
	v_pk_mul_f32 v[184:185], v[76:77], v[174:175]
	v_pk_mul_f32 v[174:175], v[178:179], v[178:179]
	v_pk_mul_f32 v[176:177], v[80:81], v[176:177]
	v_pk_fma_f32 v[186:187], v[182:183], v[182:183], v[174:175]
	v_pk_mul_f32 v[174:175], v[184:185], v[184:185]
	v_pk_mul_f32 v[170:171], v[66:67], v[170:171]
	v_pk_fma_f32 v[188:189], v[176:177], v[176:177], v[174:175]
	v_add_f32_e32 v151, v186, v187
	v_cvt_pk_bf16_f32 v174, v182, v183
	v_pk_mul_f32 v[172:173], v[70:71], v[172:173]
	v_pk_mul_f32 v[182:183], v[68:69], v[166:167]
	v_pk_mul_f32 v[166:167], v[170:171], v[170:171]
	v_add_f32_e32 v151, v188, v151
	v_pk_fma_f32 v[166:167], v[172:173], v[172:173], v[166:167]
	v_add_f32_e32 v151, v189, v151
	v_cvt_pk_bf16_f32 v175, v176, v177
	v_pk_mul_f32 v[168:169], v[72:73], v[168:169]
	v_pk_mul_f32 v[176:177], v[182:183], v[182:183]
	v_add_f32_e32 v151, v151, v166
	v_pk_fma_f32 v[176:177], v[168:169], v[168:169], v[176:177]
	v_add_f32_e32 v151, v167, v151
	v_add_f32_e32 v151, v176, v151
	v_add_f32_e32 v151, v177, v151
	ds_bpermute_b32 v153, v211, v151
	v_cvt_pk_bf16_f32 v176, v178, v179
	v_cvt_pk_bf16_f32 v177, v184, v185
	v_cvt_pk_bf16_f32 v166, v172, v173
	v_cvt_pk_bf16_f32 v167, v168, v169
	s_waitcnt lgkmcnt(0)
	v_add_f32_e32 v151, v151, v153
	ds_bpermute_b32 v153, v210, v151
	v_cvt_pk_bf16_f32 v168, v170, v171
	v_cvt_pk_bf16_f32 v169, v182, v183
	global_store_dwordx4 v[180:181], v[174:177], off sc1
	global_store_dwordx4 v[180:181], v[166:169], off offset:256 sc1
	s_and_saveexec_b64 s[38:39], s[0:1]
	s_cbranch_execz .LBB0_174
	v_lshl_add_u64 v[154:155], v[154:155], 2, s[10:11]
	s_waitcnt lgkmcnt(0)
	v_add_f32_e32 v151, v151, v153
	global_atomic_add_f32 v[154:155], v151, off
.LBB0_174:
	s_or_b64 exec, exec, s[38:39]
	v_fmamk_f32 v151, v164, 0xbdd2d3e8, v162
	v_mul_f32_e32 v151, v62, v151
	v_exp_f32_e32 v151, v151
	v_fmamk_f32 v138, v138, 0xbdd2d3e8, v162
	v_mul_f32_e32 v138, v58, v138
	v_mul_f32_e32 v165, v59, v59
	v_add_f32_e32 v151, 1.0, v151
	v_rcp_f32_e32 v164, v151
	v_mul_f32_e32 v151, v63, v63
	v_fmamk_f32 v151, v151, 0xbdd2d3e8, v162
	v_exp_f32_e32 v138, v138
	v_mul_f32_e32 v151, v63, v151
	v_fmamk_f32 v165, v165, 0xbdd2d3e8, v162
	v_exp_f32_e32 v151, v151
	v_mul_f32_e32 v165, v59, v165
	v_exp_f32_e32 v167, v165
	v_add_f32_e32 v138, 1.0, v138
	v_rcp_f32_e32 v166, v138
	v_add_f32_e32 v138, 1.0, v151
	v_mul_f32_e32 v151, v64, v64
	v_rcp_f32_e32 v165, v138
	v_add_f32_e32 v138, 1.0, v167
	v_fmamk_f32 v151, v151, 0xbdd2d3e8, v162
	v_mul_f32_e32 v167, v60, v60
	v_mul_f32_e32 v151, v64, v151
	v_fmamk_f32 v167, v167, 0xbdd2d3e8, v162
	v_exp_f32_e32 v151, v151
	v_mul_f32_e32 v167, v60, v167
	v_exp_f32_e32 v169, v167
	v_rcp_f32_e32 v167, v138
	v_add_f32_e32 v138, 1.0, v151
	v_mul_f32_e32 v151, v65, v65
	v_rcp_f32_e32 v168, v138
	v_add_f32_e32 v138, 1.0, v169
	v_fmamk_f32 v151, v151, 0xbdd2d3e8, v162
	v_mul_f32_e32 v169, v61, v61
	v_mul_f32_e32 v151, v65, v151
	v_fmamk_f32 v169, v169, 0xbdd2d3e8, v162
	v_exp_f32_e32 v151, v151
	v_mul_f32_e32 v169, v61, v169
	v_exp_f32_e32 v171, v169
	v_rcp_f32_e32 v170, v138
	v_add_f32_e32 v138, 1.0, v151
	v_rcp_f32_e32 v169, v138
	v_add_f32_e32 v138, 1.0, v171
	v_rcp_f32_e32 v171, v138
	v_mul_f32_e32 v138, v54, v54
	v_fmamk_f32 v138, v138, 0xbdd2d3e8, v162
	v_mul_f32_e32 v151, v50, v50
	v_mul_f32_e32 v138, v54, v138
	v_fmamk_f32 v151, v151, 0xbdd2d3e8, v162
	v_exp_f32_e32 v138, v138
	v_mul_f32_e32 v151, v50, v151
	v_exp_f32_e32 v151, v151
	v_pk_mul_f32 v[166:167], v[58:59], v[166:167]
	v_pk_mul_f32 v[170:171], v[60:61], v[170:171]
	v_pk_mul_f32 v[164:165], v[62:63], v[164:165]
	v_pk_mul_f32 v[168:169], v[64:65], v[168:169]
	v_pk_mul_f32 v[172:173], v[166:167], v[166:167]
	v_pk_mul_f32 v[174:175], v[170:171], v[170:171]
	v_add_f32_e32 v138, 1.0, v138
	v_pk_fma_f32 v[172:173], v[164:165], v[164:165], v[172:173]
	v_pk_fma_f32 v[174:175], v[168:169], v[168:169], v[174:175]
	v_cvt_pk_bf16_f32 v164, v164, v165
	v_cvt_pk_bf16_f32 v165, v168, v169
	v_rcp_f32_e32 v168, v138
	v_add_f32_e32 v138, 1.0, v151
	v_mul_f32_e32 v151, v55, v55
	v_fmamk_f32 v151, v151, 0xbdd2d3e8, v162
	v_mul_f32_e32 v169, v51, v51
	v_mul_f32_e32 v151, v55, v151
	v_fmamk_f32 v169, v169, 0xbdd2d3e8, v162
	v_exp_f32_e32 v151, v151
	v_mul_f32_e32 v169, v51, v169
	v_exp_f32_e32 v177, v169
	v_rcp_f32_e32 v176, v138
	v_add_f32_e32 v138, 1.0, v151
	v_mul_f32_e32 v151, v56, v56
	v_rcp_f32_e32 v169, v138
	v_add_f32_e32 v138, 1.0, v177
	v_fmamk_f32 v151, v151, 0xbdd2d3e8, v162
	v_mul_f32_e32 v177, v52, v52
	v_mul_f32_e32 v151, v56, v151
	v_fmamk_f32 v177, v177, 0xbdd2d3e8, v162
	v_exp_f32_e32 v151, v151
	v_mul_f32_e32 v177, v52, v177
	v_exp_f32_e32 v179, v177
	v_rcp_f32_e32 v177, v138
	v_add_f32_e32 v138, 1.0, v151
	v_mul_f32_e32 v151, v57, v57
	v_rcp_f32_e32 v178, v138
	v_add_f32_e32 v138, 1.0, v179
	v_fmamk_f32 v151, v151, 0xbdd2d3e8, v162
	v_mul_f32_e32 v179, v53, v53
	v_mul_f32_e32 v151, v57, v151
	v_fmamk_f32 v179, v179, 0xbdd2d3e8, v162
	v_exp_f32_e32 v151, v151
	v_mul_f32_e32 v179, v53, v179
	v_exp_f32_e32 v181, v179
	v_rcp_f32_e32 v180, v138
	v_add_f32_e32 v138, 1.0, v151
	v_rcp_f32_e32 v179, v138
	v_add_f32_e32 v138, 1.0, v181
	v_rcp_f32_e32 v181, v138
	v_pk_mul_f32 v[176:177], v[50:51], v[176:177]
	v_add_f32_e32 v138, v172, v173
	v_pk_mul_f32 v[168:169], v[54:55], v[168:169]
	v_pk_mul_f32 v[182:183], v[176:177], v[176:177]
	v_add_f32_e32 v138, v174, v138
	v_pk_mul_f32 v[180:181], v[52:53], v[180:181]
	v_pk_fma_f32 v[182:183], v[168:169], v[168:169], v[182:183]
	v_add_f32_e32 v138, v175, v138
	v_pk_mul_f32 v[178:179], v[56:57], v[178:179]
	v_pk_mul_f32 v[184:185], v[180:181], v[180:181]
	v_add_f32_e32 v138, v138, v182
	v_pk_fma_f32 v[184:185], v[178:179], v[178:179], v[184:185]
	v_add_f32_e32 v138, v183, v138
	v_add_f32_e32 v138, v184, v138
	v_add_f32_e32 v138, v185, v138
	ds_bpermute_b32 v151, v211, v138
	s_waitcnt lgkmcnt(0)
	v_ashrrev_i32_e32 v153, 31, v152
	v_lshlrev_b64 v[154:155], s29, v[152:153]
	v_lshl_add_u64 v[154:155], v[154:155], 1, v[148:149]
	v_cvt_pk_bf16_f32 v166, v166, v167
	v_add_f32_e32 v138, v138, v151
	ds_bpermute_b32 v151, v210, v138
	v_cvt_pk_bf16_f32 v167, v170, v171
	global_store_dwordx4 v[154:155], v[164:167], off sc1
	s_nop 1
	v_cvt_pk_bf16_f32 v164, v168, v169
	v_cvt_pk_bf16_f32 v165, v178, v179
	v_cvt_pk_bf16_f32 v166, v176, v177
	v_cvt_pk_bf16_f32 v167, v180, v181
	global_store_dwordx4 v[154:155], v[164:167], off offset:256 sc1
	s_and_saveexec_b64 s[38:39], s[0:1]
	s_cbranch_execz .LBB0_176
	v_lshl_add_u64 v[152:153], v[152:153], 2, s[10:11]
	s_waitcnt lgkmcnt(0)
	v_add_f32_e32 v138, v138, v151
	global_atomic_add_f32 v[152:153], v138, off
.LBB0_176:
	s_or_b64 exec, exec, s[38:39]
	v_mul_f32_e32 v138, v46, v46
	v_fmamk_f32 v138, v138, 0xbdd2d3e8, v162
	s_waitcnt lgkmcnt(0)
	v_mul_f32_e32 v151, v42, v42
	v_mul_f32_e32 v138, v46, v138
	v_fmamk_f32 v151, v151, 0xbdd2d3e8, v162
	v_exp_f32_e32 v138, v138
	v_mul_f32_e32 v151, v42, v151
	v_exp_f32_e32 v151, v151
	v_mul_f32_e32 v165, v43, v43
	v_add_f32_e32 v138, 1.0, v138
	v_rcp_f32_e32 v164, v138
	v_add_f32_e32 v138, 1.0, v151
	v_mul_f32_e32 v151, v47, v47
	v_fmamk_f32 v151, v151, 0xbdd2d3e8, v162
	v_mul_f32_e32 v151, v47, v151
	v_fmamk_f32 v165, v165, 0xbdd2d3e8, v162
	v_exp_f32_e32 v151, v151
	v_mul_f32_e32 v165, v43, v165
	v_exp_f32_e32 v167, v165
	v_rcp_f32_e32 v166, v138
	v_add_f32_e32 v138, 1.0, v151
	v_mul_f32_e32 v151, v48, v48
	v_rcp_f32_e32 v165, v138
	v_add_f32_e32 v138, 1.0, v167
	v_fmamk_f32 v151, v151, 0xbdd2d3e8, v162
	v_mul_f32_e32 v167, v44, v44
	v_mul_f32_e32 v151, v48, v151
	v_fmamk_f32 v167, v167, 0xbdd2d3e8, v162
	v_exp_f32_e32 v151, v151
	v_mul_f32_e32 v167, v44, v167
	v_exp_f32_e32 v169, v167
	v_rcp_f32_e32 v167, v138
	v_add_f32_e32 v138, 1.0, v151
	v_mul_f32_e32 v151, v49, v49
	v_rcp_f32_e32 v168, v138
	v_add_f32_e32 v138, 1.0, v169
	v_fmamk_f32 v151, v151, 0xbdd2d3e8, v162
	v_mul_f32_e32 v169, v45, v45
	v_mul_f32_e32 v151, v49, v151
	v_fmamk_f32 v169, v169, 0xbdd2d3e8, v162
	v_exp_f32_e32 v151, v151
	v_mul_f32_e32 v169, v45, v169
	v_exp_f32_e32 v171, v169
	v_rcp_f32_e32 v170, v138
	v_add_f32_e32 v138, 1.0, v151
	v_rcp_f32_e32 v169, v138
	v_add_f32_e32 v138, 1.0, v171
	v_rcp_f32_e32 v171, v138
	v_mul_f32_e32 v138, v38, v38
	v_fmamk_f32 v138, v138, 0xbdd2d3e8, v162
	v_mul_f32_e32 v151, v34, v34
	v_mul_f32_e32 v138, v38, v138
	v_fmamk_f32 v151, v151, 0xbdd2d3e8, v162
	v_exp_f32_e32 v138, v138
	v_mul_f32_e32 v151, v34, v151
	v_exp_f32_e32 v151, v151
	v_pk_mul_f32 v[166:167], v[42:43], v[166:167]
	v_pk_mul_f32 v[170:171], v[44:45], v[170:171]
	v_pk_mul_f32 v[164:165], v[46:47], v[164:165]
	v_pk_mul_f32 v[168:169], v[48:49], v[168:169]
	v_pk_mul_f32 v[172:173], v[166:167], v[166:167]
	v_pk_mul_f32 v[174:175], v[170:171], v[170:171]
	v_add_f32_e32 v138, 1.0, v138
	v_pk_fma_f32 v[172:173], v[164:165], v[164:165], v[172:173]
	v_pk_fma_f32 v[174:175], v[168:169], v[168:169], v[174:175]
	v_cvt_pk_bf16_f32 v164, v164, v165
	v_cvt_pk_bf16_f32 v165, v168, v169
	v_rcp_f32_e32 v168, v138
	v_add_f32_e32 v138, 1.0, v151
	v_mul_f32_e32 v151, v39, v39
	v_fmamk_f32 v151, v151, 0xbdd2d3e8, v162
	v_mul_f32_e32 v169, v35, v35
	v_mul_f32_e32 v151, v39, v151
	v_fmamk_f32 v169, v169, 0xbdd2d3e8, v162
	v_exp_f32_e32 v151, v151
	v_mul_f32_e32 v169, v35, v169
	v_exp_f32_e32 v177, v169
	v_rcp_f32_e32 v176, v138
	v_add_f32_e32 v138, 1.0, v151
	v_mul_f32_e32 v151, v40, v40
	v_rcp_f32_e32 v169, v138
	v_add_f32_e32 v138, 1.0, v177
	v_fmamk_f32 v151, v151, 0xbdd2d3e8, v162
	v_mul_f32_e32 v177, v36, v36
	v_mul_f32_e32 v151, v40, v151
	v_fmamk_f32 v177, v177, 0xbdd2d3e8, v162
	v_exp_f32_e32 v151, v151
	v_mul_f32_e32 v177, v36, v177
	v_exp_f32_e32 v179, v177
	v_rcp_f32_e32 v177, v138
	v_add_f32_e32 v138, 1.0, v151
	v_mul_f32_e32 v151, v41, v41
	v_rcp_f32_e32 v178, v138
	v_add_f32_e32 v138, 1.0, v179
	v_fmamk_f32 v151, v151, 0xbdd2d3e8, v162
	v_mul_f32_e32 v179, v37, v37
	v_mul_f32_e32 v151, v41, v151
	v_fmamk_f32 v179, v179, 0xbdd2d3e8, v162
	v_exp_f32_e32 v151, v151
	v_mul_f32_e32 v179, v37, v179
	v_exp_f32_e32 v181, v179
	v_rcp_f32_e32 v180, v138
	v_add_f32_e32 v138, 1.0, v151
	v_rcp_f32_e32 v179, v138
	v_add_f32_e32 v138, 1.0, v181
	v_rcp_f32_e32 v181, v138
	v_pk_mul_f32 v[176:177], v[34:35], v[176:177]
	v_add_f32_e32 v138, v172, v173
	v_pk_mul_f32 v[168:169], v[38:39], v[168:169]
	v_pk_mul_f32 v[182:183], v[176:177], v[176:177]
	v_add_f32_e32 v138, v174, v138
	v_pk_mul_f32 v[180:181], v[36:37], v[180:181]
	v_pk_fma_f32 v[182:183], v[168:169], v[168:169], v[182:183]
	v_add_f32_e32 v138, v175, v138
	v_pk_mul_f32 v[178:179], v[40:41], v[178:179]
	v_pk_mul_f32 v[184:185], v[180:181], v[180:181]
	v_add_f32_e32 v138, v138, v182
	v_pk_fma_f32 v[184:185], v[178:179], v[178:179], v[184:185]
	v_add_f32_e32 v138, v183, v138
	v_add_f32_e32 v138, v184, v138
	v_add_f32_e32 v138, v185, v138
	ds_bpermute_b32 v151, v211, v138
	v_add_u32_e32 v152, 0x90, v150
	v_ashrrev_i32_e32 v153, 31, v152
	v_lshlrev_b64 v[154:155], s29, v[152:153]
	v_lshl_add_u64 v[154:155], v[154:155], 1, v[148:149]
	s_waitcnt lgkmcnt(0)
	v_add_f32_e32 v138, v138, v151
	ds_bpermute_b32 v151, v210, v138
	v_cvt_pk_bf16_f32 v166, v166, v167
	v_cvt_pk_bf16_f32 v167, v170, v171
	global_store_dwordx4 v[154:155], v[164:167], off sc1
	s_nop 1
	v_cvt_pk_bf16_f32 v164, v168, v169
	v_cvt_pk_bf16_f32 v165, v178, v179
	v_cvt_pk_bf16_f32 v166, v176, v177
	v_cvt_pk_bf16_f32 v167, v180, v181
	global_store_dwordx4 v[154:155], v[164:167], off offset:256 sc1
	s_and_saveexec_b64 s[38:39], s[0:1]
	s_cbranch_execz .LBB0_178
	v_lshl_add_u64 v[152:153], v[152:153], 2, s[10:11]
	s_waitcnt lgkmcnt(0)
	v_add_f32_e32 v138, v138, v151
	global_atomic_add_f32 v[152:153], v138, off
.LBB0_178:
	s_or_b64 exec, exec, s[38:39]
	v_mul_f32_e32 v138, v30, v30
	v_fmamk_f32 v138, v138, 0xbdd2d3e8, v162
	s_waitcnt lgkmcnt(0)
	v_mul_f32_e32 v151, v26, v26
	v_mul_f32_e32 v138, v30, v138
	v_fmamk_f32 v151, v151, 0xbdd2d3e8, v162
	v_exp_f32_e32 v138, v138
	v_mul_f32_e32 v151, v26, v151
	v_exp_f32_e32 v151, v151
	v_mul_f32_e32 v165, v27, v27
	v_add_f32_e32 v138, 1.0, v138
	v_rcp_f32_e32 v164, v138
	v_add_f32_e32 v138, 1.0, v151
	v_mul_f32_e32 v151, v31, v31
	v_fmamk_f32 v151, v151, 0xbdd2d3e8, v162
	v_mul_f32_e32 v151, v31, v151
	v_fmamk_f32 v165, v165, 0xbdd2d3e8, v162
	v_exp_f32_e32 v151, v151
	v_mul_f32_e32 v165, v27, v165
	v_exp_f32_e32 v167, v165
	v_rcp_f32_e32 v166, v138
	v_add_f32_e32 v138, 1.0, v151
	v_mul_f32_e32 v151, v32, v32
	v_rcp_f32_e32 v165, v138
	v_add_f32_e32 v138, 1.0, v167
	v_fmamk_f32 v151, v151, 0xbdd2d3e8, v162
	v_mul_f32_e32 v167, v28, v28
	v_mul_f32_e32 v151, v32, v151
	v_fmamk_f32 v167, v167, 0xbdd2d3e8, v162
	v_exp_f32_e32 v151, v151
	v_mul_f32_e32 v167, v28, v167
	v_exp_f32_e32 v169, v167
	v_rcp_f32_e32 v167, v138
	v_add_f32_e32 v138, 1.0, v151
	v_mul_f32_e32 v151, v33, v33
	v_rcp_f32_e32 v168, v138
	v_add_f32_e32 v138, 1.0, v169
	v_fmamk_f32 v151, v151, 0xbdd2d3e8, v162
	v_mul_f32_e32 v169, v29, v29
	v_mul_f32_e32 v151, v33, v151
	v_fmamk_f32 v169, v169, 0xbdd2d3e8, v162
	v_exp_f32_e32 v151, v151
	v_mul_f32_e32 v169, v29, v169
	v_exp_f32_e32 v171, v169
	v_rcp_f32_e32 v170, v138
	v_add_f32_e32 v138, 1.0, v151
	v_rcp_f32_e32 v169, v138
	v_add_f32_e32 v138, 1.0, v171
	v_rcp_f32_e32 v171, v138
	v_mul_f32_e32 v138, v22, v22
	v_fmamk_f32 v138, v138, 0xbdd2d3e8, v162
	v_mul_f32_e32 v151, v18, v18
	v_mul_f32_e32 v138, v22, v138
	v_fmamk_f32 v151, v151, 0xbdd2d3e8, v162
	v_exp_f32_e32 v138, v138
	v_mul_f32_e32 v151, v18, v151
	v_exp_f32_e32 v151, v151
	v_pk_mul_f32 v[166:167], v[26:27], v[166:167]
	v_pk_mul_f32 v[170:171], v[28:29], v[170:171]
	v_pk_mul_f32 v[164:165], v[30:31], v[164:165]
	v_pk_mul_f32 v[168:169], v[32:33], v[168:169]
	v_pk_mul_f32 v[172:173], v[166:167], v[166:167]
	v_pk_mul_f32 v[174:175], v[170:171], v[170:171]
	v_add_f32_e32 v138, 1.0, v138
	v_pk_fma_f32 v[172:173], v[164:165], v[164:165], v[172:173]
	v_pk_fma_f32 v[174:175], v[168:169], v[168:169], v[174:175]
	v_cvt_pk_bf16_f32 v164, v164, v165
	v_cvt_pk_bf16_f32 v165, v168, v169
	v_rcp_f32_e32 v168, v138
	v_add_f32_e32 v138, 1.0, v151
	v_mul_f32_e32 v151, v23, v23
	v_fmamk_f32 v151, v151, 0xbdd2d3e8, v162
	v_mul_f32_e32 v169, v19, v19
	v_mul_f32_e32 v151, v23, v151
	v_fmamk_f32 v169, v169, 0xbdd2d3e8, v162
	v_exp_f32_e32 v151, v151
	v_mul_f32_e32 v169, v19, v169
	v_exp_f32_e32 v177, v169
	v_rcp_f32_e32 v176, v138
	v_add_f32_e32 v138, 1.0, v151
	v_mul_f32_e32 v151, v24, v24
	v_rcp_f32_e32 v169, v138
	v_add_f32_e32 v138, 1.0, v177
	v_fmamk_f32 v151, v151, 0xbdd2d3e8, v162
	v_mul_f32_e32 v177, v20, v20
	v_mul_f32_e32 v151, v24, v151
	v_fmamk_f32 v177, v177, 0xbdd2d3e8, v162
	v_exp_f32_e32 v151, v151
	v_mul_f32_e32 v177, v20, v177
	v_exp_f32_e32 v179, v177
	v_rcp_f32_e32 v177, v138
	v_add_f32_e32 v138, 1.0, v151
	v_mul_f32_e32 v151, v25, v25
	v_rcp_f32_e32 v178, v138
	v_add_f32_e32 v138, 1.0, v179
	v_fmamk_f32 v151, v151, 0xbdd2d3e8, v162
	v_mul_f32_e32 v179, v21, v21
	v_mul_f32_e32 v151, v25, v151
	v_fmamk_f32 v179, v179, 0xbdd2d3e8, v162
	v_exp_f32_e32 v151, v151
	v_mul_f32_e32 v179, v21, v179
	v_exp_f32_e32 v181, v179
	v_rcp_f32_e32 v180, v138
	v_add_f32_e32 v138, 1.0, v151
	v_rcp_f32_e32 v179, v138
	v_add_f32_e32 v138, 1.0, v181
	v_rcp_f32_e32 v181, v138
	v_pk_mul_f32 v[176:177], v[18:19], v[176:177]
	v_add_f32_e32 v138, v172, v173
	v_pk_mul_f32 v[168:169], v[22:23], v[168:169]
	v_pk_mul_f32 v[182:183], v[176:177], v[176:177]
	v_add_f32_e32 v138, v174, v138
	v_pk_mul_f32 v[180:181], v[20:21], v[180:181]
	v_pk_fma_f32 v[182:183], v[168:169], v[168:169], v[182:183]
	v_add_f32_e32 v138, v175, v138
	v_pk_mul_f32 v[178:179], v[24:25], v[178:179]
	v_pk_mul_f32 v[184:185], v[180:181], v[180:181]
	v_add_f32_e32 v138, v138, v182
	v_pk_fma_f32 v[184:185], v[178:179], v[178:179], v[184:185]
	v_add_f32_e32 v138, v183, v138
	v_add_f32_e32 v138, v184, v138
	v_add_f32_e32 v138, v185, v138
	ds_bpermute_b32 v151, v211, v138
	v_add_u32_e32 v152, 0xa0, v150
	v_ashrrev_i32_e32 v153, 31, v152
	v_lshlrev_b64 v[154:155], s29, v[152:153]
	v_lshl_add_u64 v[154:155], v[154:155], 1, v[148:149]
	s_waitcnt lgkmcnt(0)
	v_add_f32_e32 v138, v138, v151
	ds_bpermute_b32 v151, v210, v138
	v_cvt_pk_bf16_f32 v166, v166, v167
	v_cvt_pk_bf16_f32 v167, v170, v171
	global_store_dwordx4 v[154:155], v[164:167], off sc1
	s_nop 1
	v_cvt_pk_bf16_f32 v164, v168, v169
	v_cvt_pk_bf16_f32 v165, v178, v179
	v_cvt_pk_bf16_f32 v166, v176, v177
	v_cvt_pk_bf16_f32 v167, v180, v181
	global_store_dwordx4 v[154:155], v[164:167], off offset:256 sc1
	s_and_saveexec_b64 s[38:39], s[0:1]
	s_cbranch_execz .LBB0_180
	v_lshl_add_u64 v[152:153], v[152:153], 2, s[10:11]
	s_waitcnt lgkmcnt(0)
	v_add_f32_e32 v138, v138, v151
	global_atomic_add_f32 v[152:153], v138, off
.LBB0_180:
	s_or_b64 exec, exec, s[38:39]
	v_mul_f32_e32 v138, v14, v14
	v_fmamk_f32 v138, v138, 0xbdd2d3e8, v162
	s_waitcnt lgkmcnt(0)
	v_mul_f32_e32 v151, v10, v10
	v_mul_f32_e32 v138, v14, v138
	v_fmamk_f32 v151, v151, 0xbdd2d3e8, v162
	v_exp_f32_e32 v138, v138
	v_mul_f32_e32 v151, v10, v151
	v_exp_f32_e32 v151, v151
	v_mul_f32_e32 v165, v11, v11
	v_add_f32_e32 v138, 1.0, v138
	v_rcp_f32_e32 v164, v138
	v_add_f32_e32 v138, 1.0, v151
	v_mul_f32_e32 v151, v15, v15
	v_fmamk_f32 v151, v151, 0xbdd2d3e8, v162
	v_mul_f32_e32 v151, v15, v151
	v_fmamk_f32 v165, v165, 0xbdd2d3e8, v162
	v_exp_f32_e32 v151, v151
	v_mul_f32_e32 v165, v11, v165
	v_exp_f32_e32 v167, v165
	v_rcp_f32_e32 v166, v138
	v_add_f32_e32 v138, 1.0, v151
	v_mul_f32_e32 v151, v16, v16
	v_rcp_f32_e32 v165, v138
	v_add_f32_e32 v138, 1.0, v167
	v_fmamk_f32 v151, v151, 0xbdd2d3e8, v162
	v_mul_f32_e32 v167, v12, v12
	v_mul_f32_e32 v151, v16, v151
	v_fmamk_f32 v167, v167, 0xbdd2d3e8, v162
	v_exp_f32_e32 v151, v151
	v_mul_f32_e32 v167, v12, v167
	v_exp_f32_e32 v169, v167
	v_rcp_f32_e32 v167, v138
	v_add_f32_e32 v138, 1.0, v151
	v_mul_f32_e32 v151, v17, v17
	v_rcp_f32_e32 v168, v138
	v_add_f32_e32 v138, 1.0, v169
	v_fmamk_f32 v151, v151, 0xbdd2d3e8, v162
	v_mul_f32_e32 v169, v13, v13
	v_mul_f32_e32 v151, v17, v151
	v_fmamk_f32 v169, v169, 0xbdd2d3e8, v162
	v_exp_f32_e32 v151, v151
	v_mul_f32_e32 v169, v13, v169
	v_exp_f32_e32 v171, v169
	v_rcp_f32_e32 v170, v138
	v_add_f32_e32 v138, 1.0, v151
	v_rcp_f32_e32 v169, v138
	v_add_f32_e32 v138, 1.0, v171
	v_rcp_f32_e32 v171, v138
	v_mul_f32_e32 v138, v6, v6
	v_fmamk_f32 v138, v138, 0xbdd2d3e8, v162
	v_mul_f32_e32 v151, v2, v2
	v_mul_f32_e32 v138, v6, v138
	v_fmamk_f32 v151, v151, 0xbdd2d3e8, v162
	v_exp_f32_e32 v138, v138
	v_mul_f32_e32 v151, v2, v151
	v_exp_f32_e32 v151, v151
	v_pk_mul_f32 v[166:167], v[10:11], v[166:167]
	v_pk_mul_f32 v[170:171], v[12:13], v[170:171]
	v_pk_mul_f32 v[164:165], v[14:15], v[164:165]
	v_pk_mul_f32 v[168:169], v[16:17], v[168:169]
	v_pk_mul_f32 v[172:173], v[166:167], v[166:167]
	v_pk_mul_f32 v[174:175], v[170:171], v[170:171]
	v_add_f32_e32 v138, 1.0, v138
	v_pk_fma_f32 v[172:173], v[164:165], v[164:165], v[172:173]
	v_pk_fma_f32 v[174:175], v[168:169], v[168:169], v[174:175]
	v_cvt_pk_bf16_f32 v164, v164, v165
	v_cvt_pk_bf16_f32 v165, v168, v169
	v_rcp_f32_e32 v168, v138
	v_add_f32_e32 v138, 1.0, v151
	v_mul_f32_e32 v151, v7, v7
	v_fmamk_f32 v151, v151, 0xbdd2d3e8, v162
	v_mul_f32_e32 v169, v3, v3
	v_mul_f32_e32 v151, v7, v151
	v_fmamk_f32 v169, v169, 0xbdd2d3e8, v162
	v_exp_f32_e32 v151, v151
	v_mul_f32_e32 v169, v3, v169
	v_exp_f32_e32 v177, v169
	v_rcp_f32_e32 v176, v138
	v_add_f32_e32 v138, 1.0, v151
	v_mul_f32_e32 v151, v8, v8
	v_rcp_f32_e32 v169, v138
	v_add_f32_e32 v138, 1.0, v177
	v_fmamk_f32 v151, v151, 0xbdd2d3e8, v162
	v_mul_f32_e32 v177, v4, v4
	v_mul_f32_e32 v151, v8, v151
	v_fmamk_f32 v177, v177, 0xbdd2d3e8, v162
	v_exp_f32_e32 v151, v151
	v_mul_f32_e32 v177, v4, v177
	v_exp_f32_e32 v179, v177
	v_rcp_f32_e32 v177, v138
	v_add_f32_e32 v138, 1.0, v151
	v_mul_f32_e32 v151, v9, v9
	v_rcp_f32_e32 v178, v138
	v_add_f32_e32 v138, 1.0, v179
	v_fmamk_f32 v151, v151, 0xbdd2d3e8, v162
	v_mul_f32_e32 v179, v5, v5
	v_mul_f32_e32 v151, v9, v151
	v_fmamk_f32 v179, v179, 0xbdd2d3e8, v162
	v_exp_f32_e32 v151, v151
	v_mul_f32_e32 v179, v5, v179
	v_exp_f32_e32 v181, v179
	v_rcp_f32_e32 v180, v138
	v_add_f32_e32 v138, 1.0, v151
	v_rcp_f32_e32 v179, v138
	v_add_f32_e32 v138, 1.0, v181
	v_rcp_f32_e32 v181, v138
	v_pk_mul_f32 v[176:177], v[2:3], v[176:177]
	v_add_f32_e32 v138, v172, v173
	v_pk_mul_f32 v[168:169], v[6:7], v[168:169]
	v_pk_mul_f32 v[182:183], v[176:177], v[176:177]
	v_add_f32_e32 v138, v174, v138
	v_pk_mul_f32 v[180:181], v[4:5], v[180:181]
	v_pk_fma_f32 v[182:183], v[168:169], v[168:169], v[182:183]
	v_add_f32_e32 v138, v175, v138
	v_pk_mul_f32 v[178:179], v[8:9], v[178:179]
	v_pk_mul_f32 v[184:185], v[180:181], v[180:181]
	v_add_f32_e32 v138, v138, v182
	v_pk_fma_f32 v[184:185], v[178:179], v[178:179], v[184:185]
	v_add_f32_e32 v138, v183, v138
	v_add_f32_e32 v138, v184, v138
	v_add_f32_e32 v138, v185, v138
	ds_bpermute_b32 v151, v211, v138
	v_add_u32_e32 v152, 0xb0, v150
	v_ashrrev_i32_e32 v153, 31, v152
	v_lshlrev_b64 v[154:155], s29, v[152:153]
	v_lshl_add_u64 v[154:155], v[154:155], 1, v[148:149]
	s_waitcnt lgkmcnt(0)
	v_add_f32_e32 v138, v138, v151
	ds_bpermute_b32 v151, v210, v138
	v_cvt_pk_bf16_f32 v166, v166, v167
	v_cvt_pk_bf16_f32 v167, v170, v171
	global_store_dwordx4 v[154:155], v[164:167], off sc1
	s_nop 1
	v_cvt_pk_bf16_f32 v164, v168, v169
	v_cvt_pk_bf16_f32 v165, v178, v179
	v_cvt_pk_bf16_f32 v166, v176, v177
	v_cvt_pk_bf16_f32 v167, v180, v181
	global_store_dwordx4 v[154:155], v[164:167], off offset:256 sc1
	s_and_saveexec_b64 s[38:39], s[0:1]
	s_cbranch_execz .LBB0_182
	v_lshl_add_u64 v[152:153], v[152:153], 2, s[10:11]
	s_waitcnt lgkmcnt(0)
	v_add_f32_e32 v138, v138, v151
	global_atomic_add_f32 v[152:153], v138, off

.LBB0_190:
	s_cmp_gt_i32 s95, 3
	s_cselect_b64 s[0:1], -1, 0
	s_and_b64 s[4:5], s[6:7], s[0:1]
	s_andn2_b64 vcc, exec, s[4:5]
	s_cbranch_vccnz .LBB0_244
	s_waitcnt vmcnt(0) lgkmcnt(0)
	s_barrier
	s_mov_b64 s[4:5], exec
	v_readlane_b32 s6, v246, 2
	v_readlane_b32 s7, v246, 3
	s_and_b64 s[6:7], s[4:5], s[6:7]
	s_mov_b64 exec, s[6:7]
	s_cbranch_execz .Lp2w_end
	buffer_inv sc1
	s_add_u32 s6, s92, 0x55000
	s_addc_u32 s7, s93, 0
	s_and_b32 s8, s2, 15
	s_lshl_b32 s8, s8, 2
	s_add_u32 s8, s8, 0x54200
	s_add_u32 s8, s92, s8
	s_addc_u32 s9, s93, 0
	v_mov_b32_e32 v2, 0
	s_mov_b32 s10, 0x400000
	s_movk_i32 s11, 0xff
.Lp2w_poll:
	global_load_dword v3, v2, s[6:7] sc1
	s_waitcnt vmcnt(0)
	v_cmp_lt_u32_e32 vcc, s11, v3
	s_cbranch_vccnz .Lp2w_ok
	s_sleep 1
	s_sub_u32 s10, s10, 1
	s_cmp_lg_u32 s10, 0
	s_cbranch_scc1 .Lp2w_poll
.Lp2w_ok:
	global_load_dword v3, v2, s[8:9] sc1
	s_waitcnt vmcnt(0)
	v_add_u32_e32 v4, -1, v3
	v_and_b32_e32 v4, v4, v3
	v_cmp_ne_u32_e32 vcc, 0, v4
	s_cbranch_vccz .Lp2w_end
	s_add_u32 s8, s92, 0x54100
	s_addc_u32 s9, s93, 0
	v_mov_b32_e32 v4, 1
	global_atomic_add v2, v4, s[8:9]
.Lp2w_end:
	s_mov_b64 exec, s[4:5]
	s_barrier
